# combined + SALU DMA addresses also in the P4 and P6' K-loops, dead setprio pairs removed in every K-loop
# baseline (speedup 1.0000x reference)
.LBB0_296:
	ds_read_b128 v[140:143], v146
	ds_read_b128 v[152:155], v146 offset:1024
	ds_read_b128 v[156:159], v146 offset:2048
	ds_read_b128 v[160:163], v146 offset:3072
	ds_read_b128 v[164:167], v147
	ds_read_b128 v[168:171], v147 offset:1024
	ds_read_b128 v[172:175], v147 offset:2048
	ds_read_b128 v[176:179], v147 offset:3072
	s_add_u32 s21, s50, 0xfff80080
	s_addc_u32 s52, s51, -1
	s_cmp_eq_u32 s67, 12
	s_cselect_b32 s55, s17, s52
	s_cselect_b32 s54, s16, s21
	s_cselect_b32 s53, s23, s66
	s_cselect_b32 s52, s22, s45
	s_mov_b32 m0, s94
	v_lshl_add_u64 v[184:185], s[50:51], 0, v[136:137]
	ds_read_b128 v[180:183], v148
	ds_read_b128 v[188:191], v148 offset:1024
	ds_read_b128 v[192:195], v148 offset:2048
	ds_read_b128 v[196:199], v148 offset:3072
	ds_read_b128 v[200:203], v148 offset:4096
	ds_read_b128 v[204:207], v148 offset:5120
	ds_read_b128 v[208:211], v148 offset:6144
	ds_read_b128 v[212:215], v148 offset:7168
	global_load_lds_dwordx4 v[184:185], off
	v_lshl_add_u64 v[184:185], s[50:51], 0, v[138:139]
	s_mov_b32 m0, s95
	s_nop 0
	global_load_lds_dwordx4 v[184:185], off
	s_waitcnt vmcnt(8)
	s_waitcnt lgkmcnt(0)
	s_barrier
	s_setprio 1
	s_waitcnt lgkmcnt(0)
	v_mfma_f32_16x16x32_bf16 v[124:127], v[140:143], v[180:183], v[124:127]
	v_mfma_f32_16x16x32_bf16 v[120:123], v[156:159], v[180:183], v[120:123]
	v_mfma_f32_16x16x32_bf16 v[116:119], v[140:143], v[192:195], v[116:119]
	v_mfma_f32_16x16x32_bf16 v[108:111], v[156:159], v[192:195], v[108:111]
	v_mfma_f32_16x16x32_bf16 v[100:103], v[140:143], v[200:203], v[100:103]
	v_mfma_f32_16x16x32_bf16 v[92:95], v[156:159], v[200:203], v[92:95]
	v_mfma_f32_16x16x32_bf16 v[84:87], v[140:143], v[208:211], v[84:87]
	v_mfma_f32_16x16x32_bf16 v[76:79], v[156:159], v[208:211], v[76:79]
	v_mfma_f32_16x16x32_bf16 v[124:127], v[152:155], v[188:191], v[124:127]
	v_mfma_f32_16x16x32_bf16 v[120:123], v[160:163], v[188:191], v[120:123]
	v_mfma_f32_16x16x32_bf16 v[116:119], v[152:155], v[196:199], v[116:119]
	v_mfma_f32_16x16x32_bf16 v[108:111], v[160:163], v[196:199], v[108:111]
	v_mfma_f32_16x16x32_bf16 v[100:103], v[152:155], v[204:207], v[100:103]
	v_mfma_f32_16x16x32_bf16 v[92:95], v[160:163], v[204:207], v[92:95]
	v_mfma_f32_16x16x32_bf16 v[84:87], v[152:155], v[212:215], v[84:87]
	v_mfma_f32_16x16x32_bf16 v[76:79], v[160:163], v[212:215], v[76:79]
	v_mfma_f32_16x16x32_bf16 v[112:115], v[164:167], v[180:183], v[112:115]
	v_mfma_f32_16x16x32_bf16 v[104:107], v[172:175], v[180:183], v[104:107]
	v_mfma_f32_16x16x32_bf16 v[96:99], v[164:167], v[192:195], v[96:99]
	v_mfma_f32_16x16x32_bf16 v[88:91], v[172:175], v[192:195], v[88:91]
	v_mfma_f32_16x16x32_bf16 v[80:83], v[164:167], v[200:203], v[80:83]
	v_mfma_f32_16x16x32_bf16 v[72:75], v[172:175], v[200:203], v[72:75]
	v_mfma_f32_16x16x32_bf16 v[68:71], v[164:167], v[208:211], v[68:71]
	v_mfma_f32_16x16x32_bf16 v[64:67], v[172:175], v[208:211], v[64:67]
	v_mfma_f32_16x16x32_bf16 v[112:115], v[168:171], v[188:191], v[112:115]
	v_mfma_f32_16x16x32_bf16 v[104:107], v[176:179], v[188:191], v[104:107]
	v_mfma_f32_16x16x32_bf16 v[96:99], v[168:171], v[196:199], v[96:99]
	v_mfma_f32_16x16x32_bf16 v[88:91], v[176:179], v[196:199], v[88:91]
	v_mfma_f32_16x16x32_bf16 v[80:83], v[168:171], v[204:207], v[80:83]
	v_mfma_f32_16x16x32_bf16 v[72:75], v[176:179], v[204:207], v[72:75]
	v_mfma_f32_16x16x32_bf16 v[68:71], v[168:171], v[212:215], v[68:71]
	v_mfma_f32_16x16x32_bf16 v[64:67], v[176:179], v[212:215], v[64:67]
	s_setprio 0
	s_barrier
	s_mov_b32 m0, s96
	v_lshl_add_u64 v[184:185], s[52:53], 0, v[132:133]
	s_add_u32 s74, s52, 0x80000
	ds_read_b128 v[180:183], v148 offset:16384
	ds_read_b128 v[188:191], v148 offset:17408
	ds_read_b128 v[192:195], v148 offset:18432
	ds_read_b128 v[196:199], v148 offset:19456
	ds_read_b128 v[200:203], v148 offset:20480
	ds_read_b128 v[204:207], v148 offset:21504
	ds_read_b128 v[208:211], v148 offset:22528
	ds_read_b128 v[212:215], v148 offset:23552
	global_load_lds_dwordx4 v[184:185], off
	v_lshl_add_u64 v[216:217], s[52:53], 0, v[128:129]
	s_mov_b32 m0, s97
	s_addc_u32 s75, s53, 0
	global_load_lds_dwordx4 v[216:217], off
	v_lshl_add_u64 v[218:219], s[74:75], 0, v[132:133]
	s_mov_b32 m0, s91
	v_lshl_add_u64 v[220:221], s[54:55], 0, v[130:131]
	global_load_lds_dwordx4 v[218:219], off
	v_lshl_add_u64 v[218:219], s[74:75], 0, v[128:129]
	s_mov_b32 m0, s26
	s_nop 0
	global_load_lds_dwordx4 v[218:219], off
	v_lshl_add_u64 v[218:219], s[54:55], 0, v[134:135]
	s_mov_b32 m0, s33
	s_nop 0
	global_load_lds_dwordx4 v[218:219], off
	s_mov_b32 m0, s88
	s_nop 0
	global_load_lds_dwordx4 v[220:221], off
	s_waitcnt vmcnt(8)
	s_waitcnt lgkmcnt(0)
	s_barrier
	s_setprio 1
	s_waitcnt lgkmcnt(0)
	v_mfma_f32_16x16x32_bf16 v[60:63], v[140:143], v[180:183], v[60:63]
	v_mfma_f32_16x16x32_bf16 v[56:59], v[156:159], v[180:183], v[56:59]
	v_mfma_f32_16x16x32_bf16 v[52:55], v[140:143], v[192:195], v[52:55]
	v_mfma_f32_16x16x32_bf16 v[44:47], v[156:159], v[192:195], v[44:47]
	v_mfma_f32_16x16x32_bf16 v[36:39], v[140:143], v[200:203], v[36:39]
	v_mfma_f32_16x16x32_bf16 v[28:31], v[156:159], v[200:203], v[28:31]
	v_mfma_f32_16x16x32_bf16 v[20:23], v[140:143], v[208:211], v[20:23]
	v_mfma_f32_16x16x32_bf16 v[12:15], v[156:159], v[208:211], v[12:15]
	v_mfma_f32_16x16x32_bf16 v[60:63], v[152:155], v[188:191], v[60:63]
	v_mfma_f32_16x16x32_bf16 v[56:59], v[160:163], v[188:191], v[56:59]
	v_mfma_f32_16x16x32_bf16 v[52:55], v[152:155], v[196:199], v[52:55]
	v_mfma_f32_16x16x32_bf16 v[44:47], v[160:163], v[196:199], v[44:47]
	v_mfma_f32_16x16x32_bf16 v[36:39], v[152:155], v[204:207], v[36:39]
	v_mfma_f32_16x16x32_bf16 v[28:31], v[160:163], v[204:207], v[28:31]
	v_mfma_f32_16x16x32_bf16 v[20:23], v[152:155], v[212:215], v[20:23]
	v_mfma_f32_16x16x32_bf16 v[12:15], v[160:163], v[212:215], v[12:15]
	v_mfma_f32_16x16x32_bf16 v[48:51], v[164:167], v[180:183], v[48:51]
	v_mfma_f32_16x16x32_bf16 v[40:43], v[172:175], v[180:183], v[40:43]
	v_mfma_f32_16x16x32_bf16 v[32:35], v[164:167], v[192:195], v[32:35]
	v_mfma_f32_16x16x32_bf16 v[24:27], v[172:175], v[192:195], v[24:27]
	v_mfma_f32_16x16x32_bf16 v[16:19], v[164:167], v[200:203], v[16:19]
	v_mfma_f32_16x16x32_bf16 v[8:11], v[172:175], v[200:203], v[8:11]
	v_mfma_f32_16x16x32_bf16 v[4:7], v[164:167], v[208:211], v[4:7]
	v_mfma_f32_16x16x32_bf16 v[0:3], v[172:175], v[208:211], v[0:3]
	v_mfma_f32_16x16x32_bf16 v[48:51], v[168:171], v[188:191], v[48:51]
	v_mfma_f32_16x16x32_bf16 v[40:43], v[176:179], v[188:191], v[40:43]
	v_mfma_f32_16x16x32_bf16 v[32:35], v[168:171], v[196:199], v[32:35]
	v_mfma_f32_16x16x32_bf16 v[24:27], v[176:179], v[196:199], v[24:27]
	v_mfma_f32_16x16x32_bf16 v[16:19], v[168:171], v[204:207], v[16:19]
	v_mfma_f32_16x16x32_bf16 v[8:11], v[176:179], v[204:207], v[8:11]
	v_mfma_f32_16x16x32_bf16 v[4:7], v[168:171], v[212:215], v[4:7]
	v_mfma_f32_16x16x32_bf16 v[0:3], v[176:179], v[212:215], v[0:3]
	s_setprio 0
	s_barrier
	ds_read_b128 v[140:143], v149
	ds_read_b128 v[152:155], v149 offset:1024
	ds_read_b128 v[156:159], v149 offset:2048
	ds_read_b128 v[160:163], v149 offset:3072
	ds_read_b128 v[164:167], v150
	ds_read_b128 v[168:171], v150 offset:1024
	ds_read_b128 v[172:175], v150 offset:2048
	ds_read_b128 v[176:179], v150 offset:3072
	s_add_u32 s54, s54, 0x80000
	s_addc_u32 s55, s55, 0
	s_mov_b32 m0, s89
	v_lshl_add_u64 v[222:223], s[54:55], 0, v[134:135]
	ds_read_b128 v[180:183], v148 offset:32768
	ds_read_b128 v[188:191], v148 offset:33792
	ds_read_b128 v[192:195], v148 offset:34816
	ds_read_b128 v[196:199], v148 offset:35840
	ds_read_b128 v[200:203], v148 offset:36864
	ds_read_b128 v[204:207], v148 offset:37888
	ds_read_b128 v[208:211], v148 offset:38912
	ds_read_b128 v[212:215], v148 offset:39936
	global_load_lds_dwordx4 v[222:223], off
	v_lshl_add_u64 v[222:223], s[54:55], 0, v[130:131]
	s_mov_b32 m0, s90
	s_nop 0
	global_load_lds_dwordx4 v[222:223], off
	s_waitcnt vmcnt(8)
	s_waitcnt lgkmcnt(0)
	s_barrier
	s_setprio 1
	s_waitcnt lgkmcnt(0)
	v_mfma_f32_16x16x32_bf16 v[124:127], v[140:143], v[180:183], v[124:127]
	v_mfma_f32_16x16x32_bf16 v[120:123], v[156:159], v[180:183], v[120:123]
	v_mfma_f32_16x16x32_bf16 v[116:119], v[140:143], v[192:195], v[116:119]
	v_mfma_f32_16x16x32_bf16 v[108:111], v[156:159], v[192:195], v[108:111]
	v_mfma_f32_16x16x32_bf16 v[100:103], v[140:143], v[200:203], v[100:103]
	v_mfma_f32_16x16x32_bf16 v[92:95], v[156:159], v[200:203], v[92:95]
	v_mfma_f32_16x16x32_bf16 v[84:87], v[140:143], v[208:211], v[84:87]
	v_mfma_f32_16x16x32_bf16 v[76:79], v[156:159], v[208:211], v[76:79]
	v_mfma_f32_16x16x32_bf16 v[124:127], v[152:155], v[188:191], v[124:127]
	v_mfma_f32_16x16x32_bf16 v[120:123], v[160:163], v[188:191], v[120:123]
	v_mfma_f32_16x16x32_bf16 v[116:119], v[152:155], v[196:199], v[116:119]
	v_mfma_f32_16x16x32_bf16 v[108:111], v[160:163], v[196:199], v[108:111]
	v_mfma_f32_16x16x32_bf16 v[100:103], v[152:155], v[204:207], v[100:103]
	v_mfma_f32_16x16x32_bf16 v[92:95], v[160:163], v[204:207], v[92:95]
	v_mfma_f32_16x16x32_bf16 v[84:87], v[152:155], v[212:215], v[84:87]
	v_mfma_f32_16x16x32_bf16 v[76:79], v[160:163], v[212:215], v[76:79]
	v_mfma_f32_16x16x32_bf16 v[112:115], v[164:167], v[180:183], v[112:115]
	v_mfma_f32_16x16x32_bf16 v[104:107], v[172:175], v[180:183], v[104:107]
	v_mfma_f32_16x16x32_bf16 v[96:99], v[164:167], v[192:195], v[96:99]
	v_mfma_f32_16x16x32_bf16 v[88:91], v[172:175], v[192:195], v[88:91]
	v_mfma_f32_16x16x32_bf16 v[80:83], v[164:167], v[200:203], v[80:83]
	v_mfma_f32_16x16x32_bf16 v[72:75], v[172:175], v[200:203], v[72:75]
	v_mfma_f32_16x16x32_bf16 v[68:71], v[164:167], v[208:211], v[68:71]
	v_mfma_f32_16x16x32_bf16 v[64:67], v[172:175], v[208:211], v[64:67]
	v_mfma_f32_16x16x32_bf16 v[112:115], v[168:171], v[188:191], v[112:115]
	v_mfma_f32_16x16x32_bf16 v[104:107], v[176:179], v[188:191], v[104:107]
	v_mfma_f32_16x16x32_bf16 v[96:99], v[168:171], v[196:199], v[96:99]
	v_mfma_f32_16x16x32_bf16 v[88:91], v[176:179], v[196:199], v[88:91]
	v_mfma_f32_16x16x32_bf16 v[80:83], v[168:171], v[204:207], v[80:83]
	v_mfma_f32_16x16x32_bf16 v[72:75], v[176:179], v[204:207], v[72:75]
	v_mfma_f32_16x16x32_bf16 v[68:71], v[168:171], v[212:215], v[68:71]
	v_mfma_f32_16x16x32_bf16 v[64:67], v[176:179], v[212:215], v[64:67]
	s_setprio 0
	s_barrier
	s_mov_b32 m0, s27
	v_lshl_add_u64 v[184:185], v[184:185], 0, s[14:15]
	s_add_u32 s52, s52, 0x80080
	ds_read_b128 v[180:183], v148 offset:49152
	ds_read_b128 v[188:191], v148 offset:50176
	ds_read_b128 v[192:195], v148 offset:51200
	ds_read_b128 v[196:199], v148 offset:52224
	ds_read_b128 v[200:203], v148 offset:53248
	ds_read_b128 v[204:207], v148 offset:54272
	ds_read_b128 v[208:211], v148 offset:55296
	ds_read_b128 v[212:215], v148 offset:56320
	global_load_lds_dwordx4 v[184:185], off
	v_lshl_add_u64 v[184:185], v[216:217], 0, s[14:15]
	s_mov_b32 m0, s34
	s_addc_u32 s53, s53, 0
	global_load_lds_dwordx4 v[184:185], off
	v_lshl_add_u64 v[184:185], s[52:53], 0, v[132:133]
	s_mov_b32 m0, s35
	s_nop 0
	global_load_lds_dwordx4 v[184:185], off
	v_lshl_add_u64 v[184:185], s[52:53], 0, v[128:129]
	s_mov_b32 m0, s28
	s_nop 0
	global_load_lds_dwordx4 v[184:185], off
	v_lshl_add_u64 v[184:185], v[218:219], 0, s[14:15]
	s_mov_b32 m0, s92
	s_nop 0
	global_load_lds_dwordx4 v[184:185], off
	v_lshl_add_u64 v[184:185], v[220:221], 0, s[14:15]
	s_mov_b32 m0, s93
	s_nop 0
	global_load_lds_dwordx4 v[184:185], off
	s_waitcnt vmcnt(8)
	s_waitcnt lgkmcnt(0)
	s_barrier
	s_setprio 1
	s_waitcnt lgkmcnt(0)
	v_mfma_f32_16x16x32_bf16 v[60:63], v[140:143], v[180:183], v[60:63]
	v_mfma_f32_16x16x32_bf16 v[56:59], v[156:159], v[180:183], v[56:59]
	v_mfma_f32_16x16x32_bf16 v[52:55], v[140:143], v[192:195], v[52:55]
	v_mfma_f32_16x16x32_bf16 v[44:47], v[156:159], v[192:195], v[44:47]
	v_mfma_f32_16x16x32_bf16 v[36:39], v[140:143], v[200:203], v[36:39]
	v_mfma_f32_16x16x32_bf16 v[28:31], v[156:159], v[200:203], v[28:31]
	v_mfma_f32_16x16x32_bf16 v[20:23], v[140:143], v[208:211], v[20:23]
	v_mfma_f32_16x16x32_bf16 v[12:15], v[156:159], v[208:211], v[12:15]
	v_mfma_f32_16x16x32_bf16 v[60:63], v[152:155], v[188:191], v[60:63]
	v_mfma_f32_16x16x32_bf16 v[56:59], v[160:163], v[188:191], v[56:59]
	v_mfma_f32_16x16x32_bf16 v[52:55], v[152:155], v[196:199], v[52:55]
	v_mfma_f32_16x16x32_bf16 v[44:47], v[160:163], v[196:199], v[44:47]
	v_mfma_f32_16x16x32_bf16 v[36:39], v[152:155], v[204:207], v[36:39]
	v_mfma_f32_16x16x32_bf16 v[28:31], v[160:163], v[204:207], v[28:31]
	v_mfma_f32_16x16x32_bf16 v[20:23], v[152:155], v[212:215], v[20:23]
	v_mfma_f32_16x16x32_bf16 v[12:15], v[160:163], v[212:215], v[12:15]
	v_mfma_f32_16x16x32_bf16 v[48:51], v[164:167], v[180:183], v[48:51]
	v_mfma_f32_16x16x32_bf16 v[40:43], v[172:175], v[180:183], v[40:43]
	v_mfma_f32_16x16x32_bf16 v[32:35], v[164:167], v[192:195], v[32:35]
	v_mfma_f32_16x16x32_bf16 v[24:27], v[172:175], v[192:195], v[24:27]
	v_mfma_f32_16x16x32_bf16 v[16:19], v[164:167], v[200:203], v[16:19]
	v_mfma_f32_16x16x32_bf16 v[8:11], v[172:175], v[200:203], v[8:11]
	v_mfma_f32_16x16x32_bf16 v[4:7], v[164:167], v[208:211], v[4:7]
	v_mfma_f32_16x16x32_bf16 v[0:3], v[172:175], v[208:211], v[0:3]
	v_mfma_f32_16x16x32_bf16 v[48:51], v[168:171], v[188:191], v[48:51]
	v_mfma_f32_16x16x32_bf16 v[40:43], v[176:179], v[188:191], v[40:43]
	v_mfma_f32_16x16x32_bf16 v[32:35], v[168:171], v[196:199], v[32:35]
	v_mfma_f32_16x16x32_bf16 v[24:27], v[176:179], v[196:199], v[24:27]
	v_mfma_f32_16x16x32_bf16 v[16:19], v[168:171], v[204:207], v[16:19]
	v_mfma_f32_16x16x32_bf16 v[8:11], v[176:179], v[204:207], v[8:11]
	v_mfma_f32_16x16x32_bf16 v[4:7], v[168:171], v[212:215], v[4:7]
	v_mfma_f32_16x16x32_bf16 v[0:3], v[176:179], v[212:215], v[0:3]
	s_setprio 0
	s_barrier
	s_add_i32 s67, s67, 2
	s_add_u32 s50, s50, 0x100
	s_addc_u32 s51, s51, 0
	s_add_u32 s45, s45, 0x100
	s_addc_u32 s66, s66, 0
	s_cmp_gt_u32 s67, 13
	s_cbranch_scc0 .LBB0_296
	s_and_b64 vcc, exec, s[78:79]
	s_cbranch_vccz .LBB0_299
	s_barrier

.LBB0_311:
	ds_read_b128 v[0:3], v140
	ds_read_b128 v[4:7], v140 offset:1024
	s_waitcnt lgkmcnt(0)
	ds_read_b128 v[8:11], v140 offset:2048
	ds_read_b128 v[12:15], v140 offset:3072
	ds_read_b128 v[16:19], v141
	ds_read_b128 v[20:23], v141 offset:1024
	ds_read_b128 v[24:27], v141 offset:2048
	ds_read_b128 v[28:31], v141 offset:3072
	s_add_u32 s58, s46, 0x10080
	s_addc_u32 s59, s47, 0
	s_mov_b32 m0, s94
	v_lshl_add_u64 v[64:65], s[58:59], 0, v[134:135]
	ds_read_b128 v[32:35], v142
	ds_read_b128 v[36:39], v142 offset:1024
	ds_read_b128 v[40:43], v142 offset:2048
	ds_read_b128 v[44:47], v142 offset:3072
	ds_read_b128 v[48:51], v142 offset:4096
	ds_read_b128 v[52:55], v142 offset:5120
	ds_read_b128 v[56:59], v142 offset:6144
	ds_read_b128 v[60:63], v142 offset:7168
	global_load_lds_dwordx4 v[64:65], off
	v_lshl_add_u64 v[64:65], s[58:59], 0, v[130:131]
	s_mov_b32 m0, s95
	s_nop 0
	global_load_lds_dwordx4 v[64:65], off
	s_waitcnt vmcnt(8)
	s_waitcnt lgkmcnt(0)
	s_barrier
	s_setprio 1
	s_waitcnt lgkmcnt(0)
	v_mfma_f32_16x16x32_bf16 v[64:67], v[0:3], v[32:35], 0
	v_mfma_f32_16x16x32_bf16 v[68:71], v[8:11], v[32:35], 0
	v_mfma_f32_16x16x32_bf16 v[72:75], v[0:3], v[40:43], 0
	v_mfma_f32_16x16x32_bf16 v[76:79], v[8:11], v[40:43], 0
	v_mfma_f32_16x16x32_bf16 v[80:83], v[0:3], v[48:51], 0
	v_mfma_f32_16x16x32_bf16 v[84:87], v[8:11], v[48:51], 0
	v_mfma_f32_16x16x32_bf16 v[88:91], v[0:3], v[56:59], 0
	v_mfma_f32_16x16x32_bf16 v[92:95], v[8:11], v[56:59], 0
	v_mfma_f32_16x16x32_bf16 v[64:67], v[4:7], v[36:39], v[64:67]
	v_mfma_f32_16x16x32_bf16 v[68:71], v[12:15], v[36:39], v[68:71]
	v_mfma_f32_16x16x32_bf16 v[72:75], v[4:7], v[44:47], v[72:75]
	v_mfma_f32_16x16x32_bf16 v[76:79], v[12:15], v[44:47], v[76:79]
	v_mfma_f32_16x16x32_bf16 v[80:83], v[4:7], v[52:55], v[80:83]
	v_mfma_f32_16x16x32_bf16 v[84:87], v[12:15], v[52:55], v[84:87]
	v_mfma_f32_16x16x32_bf16 v[88:91], v[4:7], v[60:63], v[88:91]
	v_mfma_f32_16x16x32_bf16 v[92:95], v[12:15], v[60:63], v[92:95]
	v_mfma_f32_16x16x32_bf16 v[96:99], v[16:19], v[32:35], 0
	v_mfma_f32_16x16x32_bf16 v[32:35], v[24:27], v[32:35], 0
	v_mfma_f32_16x16x32_bf16 v[96:99], v[20:23], v[36:39], v[96:99]
	v_mfma_f32_16x16x32_bf16 v[32:35], v[28:31], v[36:39], v[32:35]
	v_mfma_f32_16x16x32_bf16 v[36:39], v[16:19], v[40:43], 0
	v_mfma_f32_16x16x32_bf16 v[40:43], v[24:27], v[40:43], 0
	v_mfma_f32_16x16x32_bf16 v[36:39], v[20:23], v[44:47], v[36:39]
	v_mfma_f32_16x16x32_bf16 v[40:43], v[28:31], v[44:47], v[40:43]
	v_mfma_f32_16x16x32_bf16 v[44:47], v[16:19], v[48:51], 0
	v_mfma_f32_16x16x32_bf16 v[48:51], v[24:27], v[48:51], 0
	v_mfma_f32_16x16x32_bf16 v[44:47], v[20:23], v[52:55], v[44:47]
	v_mfma_f32_16x16x32_bf16 v[48:51], v[28:31], v[52:55], v[48:51]
	v_mfma_f32_16x16x32_bf16 v[52:55], v[16:19], v[56:59], 0
	v_mfma_f32_16x16x32_bf16 v[56:59], v[24:27], v[56:59], 0
	v_mfma_f32_16x16x32_bf16 v[52:55], v[20:23], v[60:63], v[52:55]
	v_mfma_f32_16x16x32_bf16 v[56:59], v[28:31], v[60:63], v[56:59]
	s_setprio 0
	s_barrier
	v_lshl_add_u64 v[136:137], s[50:51], 0, v[132:133]
	s_mov_b32 m0, s96
	v_lshl_add_u64 v[146:147], v[136:137], 0, s[10:11]
	v_lshl_add_u64 v[212:213], s[50:51], 0, v[128:129]
	s_add_u32 s58, s50, 0x10100
	ds_read_b128 v[60:63], v142 offset:16384
	ds_read_b128 v[100:103], v142 offset:17408
	ds_read_b128 v[104:107], v142 offset:18432
	ds_read_b128 v[108:111], v142 offset:19456
	ds_read_b128 v[112:115], v142 offset:20480
	ds_read_b128 v[116:119], v142 offset:21504
	ds_read_b128 v[120:123], v142 offset:22528
	ds_read_b128 v[124:127], v142 offset:23552
	global_load_lds_dwordx4 v[146:147], off
	v_lshl_add_u64 v[146:147], v[212:213], 0, s[10:11]
	s_mov_b32 m0, s97
	s_addc_u32 s59, s51, 0
	global_load_lds_dwordx4 v[146:147], off
	v_lshl_add_u64 v[146:147], s[58:59], 0, v[132:133]
	s_mov_b32 m0, s91
	v_lshl_add_u64 v[214:215], s[46:47], 0, v[134:135]
	global_load_lds_dwordx4 v[146:147], off
	v_lshl_add_u64 v[146:147], s[58:59], 0, v[128:129]
	s_mov_b32 m0, s26
	v_lshl_add_u64 v[216:217], s[46:47], 0, v[130:131]
	global_load_lds_dwordx4 v[146:147], off
	v_lshl_add_u64 v[146:147], v[214:215], 0, s[10:11]
	s_mov_b32 m0, s33
	s_nop 0
	global_load_lds_dwordx4 v[146:147], off
	v_lshl_add_u64 v[146:147], v[216:217], 0, s[10:11]
	s_mov_b32 m0, s88
	s_nop 0
	global_load_lds_dwordx4 v[146:147], off
	s_waitcnt vmcnt(8)
	s_waitcnt lgkmcnt(0)
	s_barrier
	s_setprio 1
	s_waitcnt lgkmcnt(0)
	v_mfma_f32_16x16x32_bf16 v[146:149], v[0:3], v[60:63], 0
	v_mfma_f32_16x16x32_bf16 v[154:157], v[0:3], v[104:107], 0
	v_mfma_f32_16x16x32_bf16 v[162:165], v[0:3], v[112:115], 0
	v_mfma_f32_16x16x32_bf16 v[0:3], v[0:3], v[120:123], 0
	v_mfma_f32_16x16x32_bf16 v[146:149], v[4:7], v[100:103], v[146:149]
	v_mfma_f32_16x16x32_bf16 v[154:157], v[4:7], v[108:111], v[154:157]
	v_mfma_f32_16x16x32_bf16 v[162:165], v[4:7], v[116:119], v[162:165]
	v_mfma_f32_16x16x32_bf16 v[0:3], v[4:7], v[124:127], v[0:3]
	v_mfma_f32_16x16x32_bf16 v[4:7], v[8:11], v[120:123], 0
	v_mfma_f32_16x16x32_bf16 v[150:153], v[8:11], v[60:63], 0
	v_mfma_f32_16x16x32_bf16 v[158:161], v[8:11], v[104:107], 0
	v_mfma_f32_16x16x32_bf16 v[166:169], v[8:11], v[112:115], 0
	v_mfma_f32_16x16x32_bf16 v[4:7], v[12:15], v[124:127], v[4:7]
	v_mfma_f32_16x16x32_bf16 v[150:153], v[12:15], v[100:103], v[150:153]
	v_mfma_f32_16x16x32_bf16 v[158:161], v[12:15], v[108:111], v[158:161]
	v_mfma_f32_16x16x32_bf16 v[166:169], v[12:15], v[116:119], v[166:169]
	v_mfma_f32_16x16x32_bf16 v[8:11], v[16:19], v[60:63], 0
	v_mfma_f32_16x16x32_bf16 v[12:15], v[24:27], v[60:63], 0
	v_mfma_f32_16x16x32_bf16 v[8:11], v[20:23], v[100:103], v[8:11]
	v_mfma_f32_16x16x32_bf16 v[12:15], v[28:31], v[100:103], v[12:15]
	v_mfma_f32_16x16x32_bf16 v[60:63], v[16:19], v[104:107], 0
	v_mfma_f32_16x16x32_bf16 v[100:103], v[24:27], v[104:107], 0
	v_mfma_f32_16x16x32_bf16 v[104:107], v[16:19], v[112:115], 0
	v_mfma_f32_16x16x32_bf16 v[16:19], v[16:19], v[120:123], 0
	v_mfma_f32_16x16x32_bf16 v[60:63], v[20:23], v[108:111], v[60:63]
	v_mfma_f32_16x16x32_bf16 v[100:103], v[28:31], v[108:111], v[100:103]
	v_mfma_f32_16x16x32_bf16 v[104:107], v[20:23], v[116:119], v[104:107]
	v_mfma_f32_16x16x32_bf16 v[108:111], v[24:27], v[112:115], 0
	v_mfma_f32_16x16x32_bf16 v[16:19], v[20:23], v[124:127], v[16:19]
	v_mfma_f32_16x16x32_bf16 v[20:23], v[24:27], v[120:123], 0
	v_mfma_f32_16x16x32_bf16 v[108:111], v[28:31], v[116:119], v[108:111]
	v_mfma_f32_16x16x32_bf16 v[20:23], v[28:31], v[124:127], v[20:23]
	s_setprio 0
	s_barrier
	ds_read_b128 v[24:27], v143
	ds_read_b128 v[28:31], v143 offset:1024
	ds_read_b128 v[112:115], v143 offset:2048
	ds_read_b128 v[116:119], v143 offset:3072
	ds_read_b128 v[120:123], v144
	ds_read_b128 v[124:127], v144 offset:1024
	ds_read_b128 v[170:173], v144 offset:2048
	ds_read_b128 v[174:177], v144 offset:3072
	s_add_u32 s58, s46, 0x10100
	s_addc_u32 s59, s47, 0
	s_mov_b32 m0, s89
	v_lshl_add_u64 v[218:219], s[58:59], 0, v[134:135]
	ds_read_b128 v[178:181], v142 offset:32768
	ds_read_b128 v[182:185], v142 offset:33792
	ds_read_b128 v[188:191], v142 offset:34816
	ds_read_b128 v[192:195], v142 offset:35840
	ds_read_b128 v[196:199], v142 offset:36864
	ds_read_b128 v[200:203], v142 offset:37888
	ds_read_b128 v[204:207], v142 offset:38912
	ds_read_b128 v[208:211], v142 offset:39936
	global_load_lds_dwordx4 v[218:219], off
	v_lshl_add_u64 v[218:219], s[58:59], 0, v[130:131]
	s_mov_b32 m0, s90
	s_nop 0
	global_load_lds_dwordx4 v[218:219], off
	s_waitcnt vmcnt(8)
	s_waitcnt lgkmcnt(0)
	s_barrier
	s_setprio 1
	s_waitcnt lgkmcnt(0)
	v_mfma_f32_16x16x32_bf16 v[64:67], v[24:27], v[178:181], v[64:67]
	v_mfma_f32_16x16x32_bf16 v[68:71], v[112:115], v[178:181], v[68:71]
	v_mfma_f32_16x16x32_bf16 v[72:75], v[24:27], v[188:191], v[72:75]
	v_mfma_f32_16x16x32_bf16 v[76:79], v[112:115], v[188:191], v[76:79]
	v_mfma_f32_16x16x32_bf16 v[80:83], v[24:27], v[196:199], v[80:83]
	v_mfma_f32_16x16x32_bf16 v[84:87], v[112:115], v[196:199], v[84:87]
	v_mfma_f32_16x16x32_bf16 v[88:91], v[24:27], v[204:207], v[88:91]
	v_mfma_f32_16x16x32_bf16 v[92:95], v[112:115], v[204:207], v[92:95]
	v_mfma_f32_16x16x32_bf16 v[64:67], v[28:31], v[182:185], v[64:67]
	v_mfma_f32_16x16x32_bf16 v[68:71], v[116:119], v[182:185], v[68:71]
	v_mfma_f32_16x16x32_bf16 v[72:75], v[28:31], v[192:195], v[72:75]
	v_mfma_f32_16x16x32_bf16 v[76:79], v[116:119], v[192:195], v[76:79]
	v_mfma_f32_16x16x32_bf16 v[80:83], v[28:31], v[200:203], v[80:83]
	v_mfma_f32_16x16x32_bf16 v[84:87], v[116:119], v[200:203], v[84:87]
	v_mfma_f32_16x16x32_bf16 v[88:91], v[28:31], v[208:211], v[88:91]
	v_mfma_f32_16x16x32_bf16 v[92:95], v[116:119], v[208:211], v[92:95]
	v_mfma_f32_16x16x32_bf16 v[96:99], v[120:123], v[178:181], v[96:99]
	v_mfma_f32_16x16x32_bf16 v[32:35], v[170:173], v[178:181], v[32:35]
	v_mfma_f32_16x16x32_bf16 v[36:39], v[120:123], v[188:191], v[36:39]
	v_mfma_f32_16x16x32_bf16 v[40:43], v[170:173], v[188:191], v[40:43]
	v_mfma_f32_16x16x32_bf16 v[44:47], v[120:123], v[196:199], v[44:47]
	v_mfma_f32_16x16x32_bf16 v[48:51], v[170:173], v[196:199], v[48:51]
	v_mfma_f32_16x16x32_bf16 v[52:55], v[120:123], v[204:207], v[52:55]
	v_mfma_f32_16x16x32_bf16 v[56:59], v[170:173], v[204:207], v[56:59]
	v_mfma_f32_16x16x32_bf16 v[96:99], v[124:127], v[182:185], v[96:99]
	v_mfma_f32_16x16x32_bf16 v[32:35], v[174:177], v[182:185], v[32:35]
	v_mfma_f32_16x16x32_bf16 v[36:39], v[124:127], v[192:195], v[36:39]
	v_mfma_f32_16x16x32_bf16 v[40:43], v[174:177], v[192:195], v[40:43]
	v_mfma_f32_16x16x32_bf16 v[44:47], v[124:127], v[200:203], v[44:47]
	v_mfma_f32_16x16x32_bf16 v[48:51], v[174:177], v[200:203], v[48:51]
	v_mfma_f32_16x16x32_bf16 v[52:55], v[124:127], v[208:211], v[52:55]
	v_mfma_f32_16x16x32_bf16 v[56:59], v[174:177], v[208:211], v[56:59]
	s_setprio 0
	s_barrier
	s_mov_b32 m0, s27
	v_lshl_add_u64 v[136:137], v[136:137], 0, s[14:15]
	s_add_u32 s50, s50, 0x10180
	ds_read_b128 v[178:181], v142 offset:49152
	ds_read_b128 v[182:185], v142 offset:50176
	ds_read_b128 v[188:191], v142 offset:51200
	ds_read_b128 v[192:195], v142 offset:52224
	ds_read_b128 v[196:199], v142 offset:53248
	ds_read_b128 v[200:203], v142 offset:54272
	ds_read_b128 v[204:207], v142 offset:55296
	ds_read_b128 v[208:211], v142 offset:56320
	global_load_lds_dwordx4 v[136:137], off
	v_lshl_add_u64 v[136:137], v[212:213], 0, s[14:15]
	s_mov_b32 m0, s34
	s_addc_u32 s51, s51, 0
	global_load_lds_dwordx4 v[136:137], off
	v_lshl_add_u64 v[136:137], s[50:51], 0, v[132:133]
	s_mov_b32 m0, s35
	s_nop 0
	global_load_lds_dwordx4 v[136:137], off
	v_lshl_add_u64 v[136:137], s[50:51], 0, v[128:129]
	s_mov_b32 m0, s28
	s_nop 0
	global_load_lds_dwordx4 v[136:137], off
	v_lshl_add_u64 v[136:137], v[214:215], 0, s[14:15]
	s_mov_b32 m0, s92
	s_nop 0
	global_load_lds_dwordx4 v[136:137], off
	v_lshl_add_u64 v[136:137], v[216:217], 0, s[14:15]
	s_mov_b32 m0, s93
	s_nop 0
	global_load_lds_dwordx4 v[136:137], off
	s_waitcnt vmcnt(8)
	s_waitcnt lgkmcnt(0)
	s_barrier
	s_setprio 1
	s_waitcnt lgkmcnt(0)
	v_mfma_f32_16x16x32_bf16 v[0:3], v[24:27], v[204:207], v[0:3]
	v_mfma_f32_16x16x32_bf16 v[4:7], v[112:115], v[204:207], v[4:7]
	v_mfma_f32_16x16x32_bf16 v[146:149], v[24:27], v[178:181], v[146:149]
	v_mfma_f32_16x16x32_bf16 v[150:153], v[112:115], v[178:181], v[150:153]
	v_mfma_f32_16x16x32_bf16 v[154:157], v[24:27], v[188:191], v[154:157]
	v_mfma_f32_16x16x32_bf16 v[158:161], v[112:115], v[188:191], v[158:161]
	v_mfma_f32_16x16x32_bf16 v[162:165], v[24:27], v[196:199], v[162:165]
	v_mfma_f32_16x16x32_bf16 v[166:169], v[112:115], v[196:199], v[166:169]
	v_mfma_f32_16x16x32_bf16 v[0:3], v[28:31], v[208:211], v[0:3]
	v_mfma_f32_16x16x32_bf16 v[4:7], v[116:119], v[208:211], v[4:7]
	v_mfma_f32_16x16x32_bf16 v[146:149], v[28:31], v[182:185], v[146:149]
	v_mfma_f32_16x16x32_bf16 v[150:153], v[116:119], v[182:185], v[150:153]
	v_mfma_f32_16x16x32_bf16 v[154:157], v[28:31], v[192:195], v[154:157]
	v_mfma_f32_16x16x32_bf16 v[158:161], v[116:119], v[192:195], v[158:161]
	v_mfma_f32_16x16x32_bf16 v[162:165], v[28:31], v[200:203], v[162:165]
	v_mfma_f32_16x16x32_bf16 v[166:169], v[116:119], v[200:203], v[166:169]
	v_mfma_f32_16x16x32_bf16 v[8:11], v[120:123], v[178:181], v[8:11]
	v_mfma_f32_16x16x32_bf16 v[12:15], v[170:173], v[178:181], v[12:15]
	v_mfma_f32_16x16x32_bf16 v[24:27], v[120:123], v[188:191], v[60:63]
	v_mfma_f32_16x16x32_bf16 v[28:31], v[170:173], v[188:191], v[100:103]
	v_mfma_f32_16x16x32_bf16 v[60:63], v[120:123], v[196:199], v[104:107]
	v_mfma_f32_16x16x32_bf16 v[100:103], v[170:173], v[196:199], v[108:111]
	v_mfma_f32_16x16x32_bf16 v[16:19], v[120:123], v[204:207], v[16:19]
	v_mfma_f32_16x16x32_bf16 v[20:23], v[170:173], v[204:207], v[20:23]
	v_mfma_f32_16x16x32_bf16 v[8:11], v[124:127], v[182:185], v[8:11]
	v_mfma_f32_16x16x32_bf16 v[12:15], v[174:177], v[182:185], v[12:15]
	v_mfma_f32_16x16x32_bf16 v[24:27], v[124:127], v[192:195], v[24:27]
	v_mfma_f32_16x16x32_bf16 v[28:31], v[174:177], v[192:195], v[28:31]
	v_mfma_f32_16x16x32_bf16 v[60:63], v[124:127], v[200:203], v[60:63]
	v_mfma_f32_16x16x32_bf16 v[100:103], v[174:177], v[200:203], v[100:103]
	v_mfma_f32_16x16x32_bf16 v[16:19], v[124:127], v[208:211], v[16:19]
	v_mfma_f32_16x16x32_bf16 v[20:23], v[174:177], v[208:211], v[20:23]
	s_setprio 0
	s_barrier
	ds_read_b128 v[104:107], v140
	ds_read_b128 v[108:111], v140 offset:1024
	ds_read_b128 v[112:115], v140 offset:2048
	ds_read_b128 v[116:119], v140 offset:3072
	ds_read_b128 v[120:123], v141
	ds_read_b128 v[124:127], v141 offset:1024
	ds_read_b128 v[170:173], v141 offset:2048
	ds_read_b128 v[174:177], v141 offset:3072
	s_add_u32 s46, s46, 0x10180
	s_addc_u32 s47, s47, 0
	s_mov_b32 m0, s94
	v_lshl_add_u64 v[136:137], s[46:47], 0, v[134:135]
	ds_read_b128 v[178:181], v142
	ds_read_b128 v[182:185], v142 offset:1024
	ds_read_b128 v[188:191], v142 offset:2048
	ds_read_b128 v[192:195], v142 offset:3072
	ds_read_b128 v[196:199], v142 offset:4096
	ds_read_b128 v[200:203], v142 offset:5120
	ds_read_b128 v[204:207], v142 offset:6144
	ds_read_b128 v[208:211], v142 offset:7168
	global_load_lds_dwordx4 v[136:137], off
	v_lshl_add_u64 v[136:137], s[46:47], 0, v[130:131]
	s_mov_b32 m0, s95
	s_nop 0
	global_load_lds_dwordx4 v[136:137], off
	s_waitcnt vmcnt(8)
	s_waitcnt lgkmcnt(0)
	s_barrier
	s_setprio 1
	s_waitcnt lgkmcnt(0)
	v_mfma_f32_16x16x32_bf16 v[64:67], v[104:107], v[178:181], v[64:67]
	v_mfma_f32_16x16x32_bf16 v[68:71], v[112:115], v[178:181], v[68:71]
	v_mfma_f32_16x16x32_bf16 v[72:75], v[104:107], v[188:191], v[72:75]
	v_mfma_f32_16x16x32_bf16 v[76:79], v[112:115], v[188:191], v[76:79]
	v_mfma_f32_16x16x32_bf16 v[80:83], v[104:107], v[196:199], v[80:83]
	v_mfma_f32_16x16x32_bf16 v[84:87], v[112:115], v[196:199], v[84:87]
	v_mfma_f32_16x16x32_bf16 v[88:91], v[104:107], v[204:207], v[88:91]
	v_mfma_f32_16x16x32_bf16 v[64:67], v[108:111], v[182:185], v[64:67]
	v_mfma_f32_16x16x32_bf16 v[68:71], v[116:119], v[182:185], v[68:71]
	v_mfma_f32_16x16x32_bf16 v[72:75], v[108:111], v[192:195], v[72:75]
	v_mfma_f32_16x16x32_bf16 v[76:79], v[116:119], v[192:195], v[76:79]
	v_mfma_f32_16x16x32_bf16 v[80:83], v[108:111], v[200:203], v[80:83]
	v_mfma_f32_16x16x32_bf16 v[84:87], v[116:119], v[200:203], v[84:87]
	v_mfma_f32_16x16x32_bf16 v[212:215], v[108:111], v[208:211], v[88:91]
	v_mfma_f32_16x16x32_bf16 v[88:91], v[112:115], v[204:207], v[92:95]
	v_mfma_f32_16x16x32_bf16 v[216:219], v[116:119], v[208:211], v[88:91]
	v_mfma_f32_16x16x32_bf16 v[88:91], v[120:123], v[178:181], v[96:99]
	v_mfma_f32_16x16x32_bf16 v[32:35], v[170:173], v[178:181], v[32:35]
	v_mfma_f32_16x16x32_bf16 v[36:39], v[120:123], v[188:191], v[36:39]
	v_mfma_f32_16x16x32_bf16 v[40:43], v[170:173], v[188:191], v[40:43]
	v_mfma_f32_16x16x32_bf16 v[44:47], v[120:123], v[196:199], v[44:47]
	v_mfma_f32_16x16x32_bf16 v[48:51], v[170:173], v[196:199], v[48:51]
	v_mfma_f32_16x16x32_bf16 v[52:55], v[120:123], v[204:207], v[52:55]
	v_mfma_f32_16x16x32_bf16 v[96:99], v[124:127], v[182:185], v[88:91]
	v_mfma_f32_16x16x32_bf16 v[32:35], v[174:177], v[182:185], v[32:35]
	v_mfma_f32_16x16x32_bf16 v[36:39], v[124:127], v[192:195], v[36:39]
	v_mfma_f32_16x16x32_bf16 v[40:43], v[174:177], v[192:195], v[40:43]
	v_mfma_f32_16x16x32_bf16 v[44:47], v[124:127], v[200:203], v[44:47]
	v_mfma_f32_16x16x32_bf16 v[48:51], v[174:177], v[200:203], v[48:51]
	v_mfma_f32_16x16x32_bf16 v[52:55], v[124:127], v[208:211], v[52:55]
	v_mfma_f32_16x16x32_bf16 v[56:59], v[170:173], v[204:207], v[56:59]
	v_mfma_f32_16x16x32_bf16 v[178:181], v[174:177], v[208:211], v[56:59]
	s_setprio 0
	s_barrier
	s_mov_b32 m0, s96
	v_lshl_add_u64 v[136:137], s[22:23], 0, v[132:133]
	s_add_u32 s46, s22, 0x10000
	s_nop 1
	ds_read_b128 v[56:59], v142 offset:16384
	ds_read_b128 v[88:91], v142 offset:17408
	ds_read_b128 v[92:95], v142 offset:18432
	ds_read_b128 v[182:185], v142 offset:19456
	ds_read_b128 v[188:191], v142 offset:20480
	ds_read_b128 v[192:195], v142 offset:21504
	ds_read_b128 v[196:199], v142 offset:22528
	ds_read_b128 v[200:203], v142 offset:23552
	global_load_lds_dwordx4 v[136:137], off
	v_lshl_add_u64 v[248:249], s[22:23], 0, v[128:129]
	s_mov_b32 m0, s97
	s_addc_u32 s47, s23, 0
	global_load_lds_dwordx4 v[248:249], off
	v_lshl_add_u64 v[204:205], s[46:47], 0, v[132:133]
	s_mov_b32 m0, s91
	v_lshl_add_u64 v[250:251], s[16:17], 0, v[134:135]
	global_load_lds_dwordx4 v[204:205], off
	v_lshl_add_u64 v[204:205], s[46:47], 0, v[128:129]
	s_mov_b32 m0, s26
	v_lshl_add_u64 v[252:253], s[16:17], 0, v[130:131]
	global_load_lds_dwordx4 v[204:205], off
	s_mov_b32 m0, s33
	s_nop 0
	global_load_lds_dwordx4 v[250:251], off
	s_mov_b32 m0, s88
	s_nop 0
	global_load_lds_dwordx4 v[252:253], off
	s_waitcnt vmcnt(8)
	s_waitcnt lgkmcnt(0)
	s_barrier
	s_setprio 1
	s_waitcnt lgkmcnt(0)
	v_mfma_f32_16x16x32_bf16 v[0:3], v[104:107], v[196:199], v[0:3]
	v_mfma_f32_16x16x32_bf16 v[4:7], v[112:115], v[196:199], v[4:7]
	v_mfma_f32_16x16x32_bf16 v[146:149], v[104:107], v[56:59], v[146:149]
	v_mfma_f32_16x16x32_bf16 v[150:153], v[112:115], v[56:59], v[150:153]
	v_mfma_f32_16x16x32_bf16 v[154:157], v[104:107], v[92:95], v[154:157]
	v_mfma_f32_16x16x32_bf16 v[158:161], v[112:115], v[92:95], v[158:161]
	v_mfma_f32_16x16x32_bf16 v[162:165], v[104:107], v[188:191], v[162:165]
	v_mfma_f32_16x16x32_bf16 v[166:169], v[112:115], v[188:191], v[166:169]
	v_mfma_f32_16x16x32_bf16 v[0:3], v[108:111], v[200:203], v[0:3]
	v_mfma_f32_16x16x32_bf16 v[4:7], v[116:119], v[200:203], v[4:7]
	v_mfma_f32_16x16x32_bf16 v[146:149], v[108:111], v[88:91], v[146:149]
	v_mfma_f32_16x16x32_bf16 v[150:153], v[116:119], v[88:91], v[150:153]
	v_mfma_f32_16x16x32_bf16 v[154:157], v[108:111], v[182:185], v[154:157]
	v_mfma_f32_16x16x32_bf16 v[158:161], v[116:119], v[182:185], v[158:161]
	v_mfma_f32_16x16x32_bf16 v[162:165], v[108:111], v[192:195], v[162:165]
	v_mfma_f32_16x16x32_bf16 v[166:169], v[116:119], v[192:195], v[166:169]
	v_mfma_f32_16x16x32_bf16 v[8:11], v[120:123], v[56:59], v[8:11]
	v_mfma_f32_16x16x32_bf16 v[204:207], v[124:127], v[88:91], v[8:11]
	v_mfma_f32_16x16x32_bf16 v[8:11], v[170:173], v[56:59], v[12:15]
	v_mfma_f32_16x16x32_bf16 v[208:211], v[174:177], v[88:91], v[8:11]
	v_mfma_f32_16x16x32_bf16 v[8:11], v[120:123], v[92:95], v[24:27]
	v_mfma_f32_16x16x32_bf16 v[220:223], v[124:127], v[182:185], v[8:11]
	v_mfma_f32_16x16x32_bf16 v[8:11], v[170:173], v[92:95], v[28:31]
	v_mfma_f32_16x16x32_bf16 v[182:185], v[174:177], v[182:185], v[8:11]
	v_mfma_f32_16x16x32_bf16 v[8:11], v[120:123], v[188:191], v[60:63]
	v_mfma_f32_16x16x32_bf16 v[224:227], v[124:127], v[192:195], v[8:11]
	v_mfma_f32_16x16x32_bf16 v[8:11], v[170:173], v[188:191], v[100:103]
	v_mfma_f32_16x16x32_bf16 v[188:191], v[174:177], v[192:195], v[8:11]
	v_mfma_f32_16x16x32_bf16 v[8:11], v[120:123], v[196:199], v[16:19]
	v_mfma_f32_16x16x32_bf16 v[192:195], v[124:127], v[200:203], v[8:11]
	v_mfma_f32_16x16x32_bf16 v[8:11], v[170:173], v[196:199], v[20:23]
	v_mfma_f32_16x16x32_bf16 v[170:173], v[174:177], v[200:203], v[8:11]
	s_setprio 0
	s_barrier
	s_nop 4
	ds_read_b128 v[8:11], v143
	ds_read_b128 v[12:15], v143 offset:1024
	ds_read_b128 v[16:19], v143 offset:2048
	ds_read_b128 v[20:23], v143 offset:3072
	ds_read_b128 v[174:177], v144
	ds_read_b128 v[196:199], v144 offset:1024
	ds_read_b128 v[200:203], v144 offset:2048
	ds_read_b128 v[228:231], v144 offset:3072
	s_add_u32 s46, s16, 0x10000
	s_addc_u32 s47, s17, 0
	s_mov_b32 m0, s89
	v_lshl_add_u64 v[88:89], s[46:47], 0, v[134:135]
	ds_read_b128 v[24:27], v142 offset:32768
	ds_read_b128 v[28:31], v142 offset:33792
	ds_read_b128 v[56:59], v142 offset:34816
	ds_read_b128 v[60:63], v142 offset:35840
	ds_read_b128 v[232:235], v142 offset:36864
	ds_read_b128 v[236:239], v142 offset:37888
	ds_read_b128 v[240:243], v142 offset:38912
	ds_read_b128 v[244:247], v142 offset:39936
	global_load_lds_dwordx4 v[88:89], off
	v_lshl_add_u64 v[88:89], s[46:47], 0, v[130:131]
	s_mov_b32 m0, s90
	s_nop 0
	global_load_lds_dwordx4 v[88:89], off
	s_waitcnt vmcnt(8)
	s_waitcnt lgkmcnt(0)
	s_barrier
	s_setprio 1
	s_waitcnt lgkmcnt(0)
	v_mfma_f32_16x16x32_bf16 v[64:67], v[8:11], v[24:27], v[64:67]
	v_mfma_f32_16x16x32_bf16 v[124:127], v[12:15], v[28:31], v[64:67]
	v_mfma_f32_16x16x32_bf16 v[64:67], v[16:19], v[24:27], v[68:71]
	v_mfma_f32_16x16x32_bf16 v[120:123], v[20:23], v[28:31], v[64:67]
	v_mfma_f32_16x16x32_bf16 v[64:67], v[8:11], v[56:59], v[72:75]
	v_mfma_f32_16x16x32_bf16 v[108:111], v[12:15], v[60:63], v[64:67]
	v_mfma_f32_16x16x32_bf16 v[64:67], v[16:19], v[56:59], v[76:79]
	v_mfma_f32_16x16x32_bf16 v[104:107], v[20:23], v[60:63], v[64:67]
	v_mfma_f32_16x16x32_bf16 v[64:67], v[8:11], v[232:235], v[80:83]
	v_mfma_f32_16x16x32_bf16 v[92:95], v[12:15], v[236:239], v[64:67]
	v_mfma_f32_16x16x32_bf16 v[64:67], v[16:19], v[232:235], v[84:87]
	v_mfma_f32_16x16x32_bf16 v[88:91], v[20:23], v[236:239], v[64:67]
	v_mfma_f32_16x16x32_bf16 v[64:67], v[8:11], v[240:243], v[212:215]
	v_mfma_f32_16x16x32_bf16 v[72:75], v[12:15], v[244:247], v[64:67]
	v_mfma_f32_16x16x32_bf16 v[64:67], v[16:19], v[240:243], v[216:219]
	v_mfma_f32_16x16x32_bf16 v[64:67], v[20:23], v[244:247], v[64:67]
	v_mfma_f32_16x16x32_bf16 v[68:71], v[174:177], v[24:27], v[96:99]
	v_mfma_f32_16x16x32_bf16 v[24:27], v[200:203], v[24:27], v[32:35]
	v_mfma_f32_16x16x32_bf16 v[112:115], v[228:231], v[28:31], v[24:27]
	v_mfma_f32_16x16x32_bf16 v[24:27], v[174:177], v[56:59], v[36:39]
	v_mfma_f32_16x16x32_bf16 v[100:103], v[196:199], v[60:63], v[24:27]
	v_mfma_f32_16x16x32_bf16 v[24:27], v[200:203], v[56:59], v[40:43]
	v_mfma_f32_16x16x32_bf16 v[96:99], v[228:231], v[60:63], v[24:27]
	v_mfma_f32_16x16x32_bf16 v[24:27], v[174:177], v[232:235], v[44:47]
	v_mfma_f32_16x16x32_bf16 v[84:87], v[196:199], v[236:239], v[24:27]
	v_mfma_f32_16x16x32_bf16 v[24:27], v[200:203], v[232:235], v[48:51]
	v_mfma_f32_16x16x32_bf16 v[80:83], v[228:231], v[236:239], v[24:27]
	v_mfma_f32_16x16x32_bf16 v[24:27], v[174:177], v[240:243], v[52:55]
	v_mfma_f32_16x16x32_bf16 v[56:59], v[196:199], v[244:247], v[24:27]
	v_mfma_f32_16x16x32_bf16 v[24:27], v[200:203], v[240:243], v[178:181]
	v_mfma_f32_16x16x32_bf16 v[116:119], v[196:199], v[28:31], v[68:71]
	v_mfma_f32_16x16x32_bf16 v[48:51], v[228:231], v[244:247], v[24:27]
	s_setprio 0
	s_barrier
	s_mov_b32 m0, s27
	s_nop 2
	v_lshl_add_u64 v[24:25], v[136:137], 0, s[8:9]
	s_add_u32 s46, s22, 0x10080
	ds_read_b128 v[32:35], v142 offset:49152
	ds_read_b128 v[36:39], v142 offset:50176
	ds_read_b128 v[178:181], v142 offset:51200
	ds_read_b128 v[212:215], v142 offset:52224
	ds_read_b128 v[216:219], v142 offset:53248
	ds_read_b128 v[232:235], v142 offset:54272
	ds_read_b128 v[236:239], v142 offset:55296
	ds_read_b128 v[240:243], v142 offset:56320
	global_load_lds_dwordx4 v[24:25], off
	v_lshl_add_u64 v[24:25], v[248:249], 0, s[8:9]
	s_mov_b32 m0, s34
	s_addc_u32 s47, s23, 0
	global_load_lds_dwordx4 v[24:25], off
	v_lshl_add_u64 v[24:25], s[46:47], 0, v[132:133]
	s_mov_b32 m0, s35
	s_nop 0
	global_load_lds_dwordx4 v[24:25], off
	v_lshl_add_u64 v[24:25], s[46:47], 0, v[128:129]
	s_mov_b32 m0, s28
	s_nop 0
	global_load_lds_dwordx4 v[24:25], off
	v_lshl_add_u64 v[24:25], v[250:251], 0, s[8:9]
	s_mov_b32 m0, s92
	s_nop 0
	global_load_lds_dwordx4 v[24:25], off
	v_lshl_add_u64 v[24:25], v[252:253], 0, s[8:9]
	s_mov_b32 m0, s93
	s_nop 0
	global_load_lds_dwordx4 v[24:25], off
	s_waitcnt vmcnt(8)
	s_waitcnt lgkmcnt(0)
	s_barrier
	s_setprio 1
	s_waitcnt lgkmcnt(0)
	v_mfma_f32_16x16x32_bf16 v[24:27], v[8:11], v[32:35], v[146:149]
	v_mfma_f32_16x16x32_bf16 v[76:79], v[12:15], v[36:39], v[24:27]
	v_mfma_f32_16x16x32_bf16 v[24:27], v[16:19], v[32:35], v[150:153]
	v_mfma_f32_16x16x32_bf16 v[68:71], v[20:23], v[36:39], v[24:27]
	v_mfma_f32_16x16x32_bf16 v[24:27], v[8:11], v[178:181], v[154:157]
	v_mfma_f32_16x16x32_bf16 v[44:47], v[12:15], v[212:215], v[24:27]
	v_mfma_f32_16x16x32_bf16 v[24:27], v[16:19], v[178:181], v[158:161]
	v_mfma_f32_16x16x32_bf16 v[40:43], v[20:23], v[212:215], v[24:27]
	v_mfma_f32_16x16x32_bf16 v[24:27], v[8:11], v[216:219], v[162:165]
	v_mfma_f32_16x16x32_bf16 v[0:3], v[8:11], v[236:239], v[0:3]
	v_mfma_f32_16x16x32_bf16 v[28:31], v[12:15], v[232:235], v[24:27]
	v_mfma_f32_16x16x32_bf16 v[24:27], v[16:19], v[216:219], v[166:169]
	v_mfma_f32_16x16x32_bf16 v[12:15], v[12:15], v[240:243], v[0:3]
	v_mfma_f32_16x16x32_bf16 v[0:3], v[16:19], v[236:239], v[4:7]
	v_mfma_f32_16x16x32_bf16 v[24:27], v[20:23], v[232:235], v[24:27]
	v_mfma_f32_16x16x32_bf16 v[8:11], v[20:23], v[240:243], v[0:3]
	v_mfma_f32_16x16x32_bf16 v[0:3], v[174:177], v[32:35], v[204:207]
	v_mfma_f32_16x16x32_bf16 v[60:63], v[196:199], v[36:39], v[0:3]
	v_mfma_f32_16x16x32_bf16 v[0:3], v[200:203], v[32:35], v[208:211]
	v_mfma_f32_16x16x32_bf16 v[52:55], v[228:231], v[36:39], v[0:3]
	v_mfma_f32_16x16x32_bf16 v[0:3], v[174:177], v[178:181], v[220:223]
	v_mfma_f32_16x16x32_bf16 v[36:39], v[196:199], v[212:215], v[0:3]
	v_mfma_f32_16x16x32_bf16 v[0:3], v[200:203], v[178:181], v[182:185]
	v_mfma_f32_16x16x32_bf16 v[32:35], v[228:231], v[212:215], v[0:3]
	v_mfma_f32_16x16x32_bf16 v[0:3], v[174:177], v[216:219], v[224:227]
	v_mfma_f32_16x16x32_bf16 v[20:23], v[196:199], v[232:235], v[0:3]
	v_mfma_f32_16x16x32_bf16 v[0:3], v[200:203], v[216:219], v[188:191]
	v_mfma_f32_16x16x32_bf16 v[16:19], v[228:231], v[232:235], v[0:3]
	v_mfma_f32_16x16x32_bf16 v[0:3], v[174:177], v[236:239], v[192:195]
	v_mfma_f32_16x16x32_bf16 v[4:7], v[196:199], v[240:243], v[0:3]
	v_mfma_f32_16x16x32_bf16 v[0:3], v[200:203], v[236:239], v[170:173]
	v_mfma_f32_16x16x32_bf16 v[0:3], v[228:231], v[240:243], v[0:3]
	s_setprio 0
	s_barrier
	s_and_b64 vcc, exec, s[4:5]
	s_cbranch_vccnz .LBB0_313
	s_barrier

.LBB0_413:
	ds_read_b128 v[144:147], v155
	ds_read_b128 v[148:151], v155 offset:1024
	ds_read_b128 v[158:161], v155 offset:2048
	ds_read_b128 v[162:165], v155 offset:3072
	ds_read_b128 v[166:169], v156
	ds_read_b128 v[170:173], v156 offset:1024
	ds_read_b128 v[174:177], v156 offset:2048
	ds_read_b128 v[178:181], v156 offset:3072
	s_add_u32 s21, s50, 0xfff80080
	s_addc_u32 s52, s51, -1
	s_cmp_eq_u32 s45, 28
	s_cselect_b32 s55, s9, s52
	s_cselect_b32 s54, s8, s21
	s_cselect_b32 s53, s43, s25
	s_cselect_b32 s52, s42, s23
	s_add_u32 s58, s52, 0x80000
	s_addc_u32 s59, s53, 0
	s_mov_b32 m0, s94
	ds_read_b128 v[182:185], v157
	ds_read_b128 v[188:191], v157 offset:1024
	ds_read_b128 v[192:195], v157 offset:2048
	ds_read_b128 v[196:199], v157 offset:3072
	ds_read_b128 v[200:203], v157 offset:4096
	ds_read_b128 v[204:207], v157 offset:5120
	ds_read_b128 v[208:211], v157 offset:6144
	ds_read_b128 v[212:215], v157 offset:7168
	global_load_lds_dwordx4 v136, s[50:51]
	s_mov_b32 m0, s95
	s_nop 0
	global_load_lds_dwordx4 v138, s[50:51]
	s_waitcnt vmcnt(8)
	s_waitcnt lgkmcnt(0)
	s_barrier
	s_setprio 1
	s_waitcnt lgkmcnt(0)
	v_mfma_f32_16x16x32_bf16 v[124:127], v[144:147], v[182:185], v[124:127]
	v_mfma_f32_16x16x32_bf16 v[120:123], v[158:161], v[182:185], v[120:123]
	v_mfma_f32_16x16x32_bf16 v[108:111], v[144:147], v[192:195], v[108:111]
	v_mfma_f32_16x16x32_bf16 v[104:107], v[158:161], v[192:195], v[104:107]
	v_mfma_f32_16x16x32_bf16 v[92:95], v[144:147], v[200:203], v[92:95]
	v_mfma_f32_16x16x32_bf16 v[88:91], v[158:161], v[200:203], v[88:91]
	v_mfma_f32_16x16x32_bf16 v[76:79], v[144:147], v[208:211], v[76:79]
	v_mfma_f32_16x16x32_bf16 v[72:75], v[158:161], v[208:211], v[72:75]
	v_mfma_f32_16x16x32_bf16 v[124:127], v[148:151], v[188:191], v[124:127]
	v_mfma_f32_16x16x32_bf16 v[120:123], v[162:165], v[188:191], v[120:123]
	v_mfma_f32_16x16x32_bf16 v[108:111], v[148:151], v[196:199], v[108:111]
	v_mfma_f32_16x16x32_bf16 v[104:107], v[162:165], v[196:199], v[104:107]
	v_mfma_f32_16x16x32_bf16 v[92:95], v[148:151], v[204:207], v[92:95]
	v_mfma_f32_16x16x32_bf16 v[88:91], v[162:165], v[204:207], v[88:91]
	v_mfma_f32_16x16x32_bf16 v[76:79], v[148:151], v[212:215], v[76:79]
	v_mfma_f32_16x16x32_bf16 v[72:75], v[162:165], v[212:215], v[72:75]
	v_mfma_f32_16x16x32_bf16 v[116:119], v[166:169], v[182:185], v[116:119]
	v_mfma_f32_16x16x32_bf16 v[112:115], v[174:177], v[182:185], v[112:115]
	v_mfma_f32_16x16x32_bf16 v[100:103], v[166:169], v[192:195], v[100:103]
	v_mfma_f32_16x16x32_bf16 v[96:99], v[174:177], v[192:195], v[96:99]
	v_mfma_f32_16x16x32_bf16 v[84:87], v[166:169], v[200:203], v[84:87]
	v_mfma_f32_16x16x32_bf16 v[80:83], v[174:177], v[200:203], v[80:83]
	v_mfma_f32_16x16x32_bf16 v[68:71], v[166:169], v[208:211], v[68:71]
	v_mfma_f32_16x16x32_bf16 v[64:67], v[174:177], v[208:211], v[64:67]
	v_mfma_f32_16x16x32_bf16 v[116:119], v[170:173], v[188:191], v[116:119]
	v_mfma_f32_16x16x32_bf16 v[112:115], v[178:181], v[188:191], v[112:115]
	v_mfma_f32_16x16x32_bf16 v[100:103], v[170:173], v[196:199], v[100:103]
	v_mfma_f32_16x16x32_bf16 v[96:99], v[178:181], v[196:199], v[96:99]
	v_mfma_f32_16x16x32_bf16 v[84:87], v[170:173], v[204:207], v[84:87]
	v_mfma_f32_16x16x32_bf16 v[80:83], v[178:181], v[204:207], v[80:83]
	v_mfma_f32_16x16x32_bf16 v[68:71], v[170:173], v[212:215], v[68:71]
	v_mfma_f32_16x16x32_bf16 v[64:67], v[178:181], v[212:215], v[64:67]
	s_setprio 0
	s_barrier
	s_mov_b32 m0, s96
	s_add_u32 s98, s54, 0x80000
	s_addc_u32 s99, s55, 0
	ds_read_b128 v[182:185], v157 offset:16384
	ds_read_b128 v[188:191], v157 offset:17408
	ds_read_b128 v[192:195], v157 offset:18432
	ds_read_b128 v[196:199], v157 offset:19456
	ds_read_b128 v[200:203], v157 offset:20480
	ds_read_b128 v[204:207], v157 offset:21504
	ds_read_b128 v[208:211], v157 offset:22528
	ds_read_b128 v[212:215], v157 offset:23552
	global_load_lds_dwordx4 v130, s[52:53]
	s_mov_b32 m0, s97
	s_nop 0
	global_load_lds_dwordx4 v134, s[52:53]
	s_mov_b32 m0, s91
	s_nop 0
	global_load_lds_dwordx4 v130, s[58:59]
	s_mov_b32 m0, s26
	s_nop 0
	global_load_lds_dwordx4 v134, s[58:59]
	s_mov_b32 m0, s33
	s_nop 0
	global_load_lds_dwordx4 v128, s[54:55]
	s_mov_b32 m0, s88
	s_nop 0
	global_load_lds_dwordx4 v132, s[54:55]
	s_waitcnt vmcnt(8)
	s_waitcnt lgkmcnt(0)
	s_barrier
	s_setprio 1
	s_waitcnt lgkmcnt(0)
	v_mfma_f32_16x16x32_bf16 v[60:63], v[144:147], v[182:185], v[60:63]
	v_mfma_f32_16x16x32_bf16 v[56:59], v[158:161], v[182:185], v[56:59]
	v_mfma_f32_16x16x32_bf16 v[44:47], v[144:147], v[192:195], v[44:47]
	v_mfma_f32_16x16x32_bf16 v[40:43], v[158:161], v[192:195], v[40:43]
	v_mfma_f32_16x16x32_bf16 v[28:31], v[144:147], v[200:203], v[28:31]
	v_mfma_f32_16x16x32_bf16 v[24:27], v[158:161], v[200:203], v[24:27]
	v_mfma_f32_16x16x32_bf16 v[12:15], v[144:147], v[208:211], v[12:15]
	v_mfma_f32_16x16x32_bf16 v[8:11], v[158:161], v[208:211], v[8:11]
	v_mfma_f32_16x16x32_bf16 v[60:63], v[148:151], v[188:191], v[60:63]
	v_mfma_f32_16x16x32_bf16 v[56:59], v[162:165], v[188:191], v[56:59]
	v_mfma_f32_16x16x32_bf16 v[44:47], v[148:151], v[196:199], v[44:47]
	v_mfma_f32_16x16x32_bf16 v[40:43], v[162:165], v[196:199], v[40:43]
	v_mfma_f32_16x16x32_bf16 v[28:31], v[148:151], v[204:207], v[28:31]
	v_mfma_f32_16x16x32_bf16 v[24:27], v[162:165], v[204:207], v[24:27]
	v_mfma_f32_16x16x32_bf16 v[12:15], v[148:151], v[212:215], v[12:15]
	v_mfma_f32_16x16x32_bf16 v[8:11], v[162:165], v[212:215], v[8:11]
	v_mfma_f32_16x16x32_bf16 v[52:55], v[166:169], v[182:185], v[52:55]
	v_mfma_f32_16x16x32_bf16 v[48:51], v[174:177], v[182:185], v[48:51]
	v_mfma_f32_16x16x32_bf16 v[36:39], v[166:169], v[192:195], v[36:39]
	v_mfma_f32_16x16x32_bf16 v[32:35], v[174:177], v[192:195], v[32:35]
	v_mfma_f32_16x16x32_bf16 v[20:23], v[166:169], v[200:203], v[20:23]
	v_mfma_f32_16x16x32_bf16 v[16:19], v[174:177], v[200:203], v[16:19]
	v_mfma_f32_16x16x32_bf16 v[4:7], v[166:169], v[208:211], v[4:7]
	v_mfma_f32_16x16x32_bf16 v[0:3], v[174:177], v[208:211], v[0:3]
	v_mfma_f32_16x16x32_bf16 v[52:55], v[170:173], v[188:191], v[52:55]
	v_mfma_f32_16x16x32_bf16 v[48:51], v[178:181], v[188:191], v[48:51]
	v_mfma_f32_16x16x32_bf16 v[36:39], v[170:173], v[196:199], v[36:39]
	v_mfma_f32_16x16x32_bf16 v[32:35], v[178:181], v[196:199], v[32:35]
	v_mfma_f32_16x16x32_bf16 v[20:23], v[170:173], v[204:207], v[20:23]
	v_mfma_f32_16x16x32_bf16 v[16:19], v[178:181], v[204:207], v[16:19]
	v_mfma_f32_16x16x32_bf16 v[4:7], v[170:173], v[212:215], v[4:7]
	v_mfma_f32_16x16x32_bf16 v[0:3], v[178:181], v[212:215], v[0:3]
	s_setprio 0
	s_barrier
	v_add_u32_e32 v162, s29, v153
	v_add_u32_e32 v178, s41, v153
	ds_read_b128 v[144:147], v162
	ds_read_b128 v[148:151], v162 offset:1024
	ds_read_b128 v[158:161], v162 offset:2048
	ds_read_b128 v[162:165], v162 offset:3072
	ds_read_b128 v[166:169], v178
	ds_read_b128 v[170:173], v178 offset:1024
	ds_read_b128 v[174:177], v178 offset:2048
	ds_read_b128 v[178:181], v178 offset:3072
	s_mov_b32 m0, s89
	s_add_u32 s100, s52, 0x80
	s_addc_u32 s101, s53, 0
	ds_read_b128 v[182:185], v157 offset:32768
	ds_read_b128 v[188:191], v157 offset:33792
	ds_read_b128 v[192:195], v157 offset:34816
	ds_read_b128 v[196:199], v157 offset:35840
	ds_read_b128 v[200:203], v157 offset:36864
	ds_read_b128 v[204:207], v157 offset:37888
	ds_read_b128 v[208:211], v157 offset:38912
	ds_read_b128 v[212:215], v157 offset:39936
	global_load_lds_dwordx4 v128, s[98:99]
	s_mov_b32 m0, s90
	s_add_u32 s58, s52, 0x80080
	s_addc_u32 s59, s53, 0
	global_load_lds_dwordx4 v132, s[98:99]
	s_add_u32 s98, s54, 0x80
	s_addc_u32 s99, s55, 0
	s_waitcnt vmcnt(8)
	s_waitcnt lgkmcnt(0)
	s_barrier
	s_setprio 1
	s_waitcnt lgkmcnt(0)
	v_mfma_f32_16x16x32_bf16 v[124:127], v[144:147], v[182:185], v[124:127]
	v_mfma_f32_16x16x32_bf16 v[120:123], v[158:161], v[182:185], v[120:123]
	v_mfma_f32_16x16x32_bf16 v[108:111], v[144:147], v[192:195], v[108:111]
	v_mfma_f32_16x16x32_bf16 v[104:107], v[158:161], v[192:195], v[104:107]
	v_mfma_f32_16x16x32_bf16 v[92:95], v[144:147], v[200:203], v[92:95]
	v_mfma_f32_16x16x32_bf16 v[88:91], v[158:161], v[200:203], v[88:91]
	v_mfma_f32_16x16x32_bf16 v[76:79], v[144:147], v[208:211], v[76:79]
	v_mfma_f32_16x16x32_bf16 v[72:75], v[158:161], v[208:211], v[72:75]
	v_mfma_f32_16x16x32_bf16 v[124:127], v[148:151], v[188:191], v[124:127]
	v_mfma_f32_16x16x32_bf16 v[120:123], v[162:165], v[188:191], v[120:123]
	v_mfma_f32_16x16x32_bf16 v[108:111], v[148:151], v[196:199], v[108:111]
	v_mfma_f32_16x16x32_bf16 v[104:107], v[162:165], v[196:199], v[104:107]
	v_mfma_f32_16x16x32_bf16 v[92:95], v[148:151], v[204:207], v[92:95]
	v_mfma_f32_16x16x32_bf16 v[88:91], v[162:165], v[204:207], v[88:91]
	v_mfma_f32_16x16x32_bf16 v[76:79], v[148:151], v[212:215], v[76:79]
	v_mfma_f32_16x16x32_bf16 v[72:75], v[162:165], v[212:215], v[72:75]
	v_mfma_f32_16x16x32_bf16 v[116:119], v[166:169], v[182:185], v[116:119]
	v_mfma_f32_16x16x32_bf16 v[112:115], v[174:177], v[182:185], v[112:115]
	v_mfma_f32_16x16x32_bf16 v[100:103], v[166:169], v[192:195], v[100:103]
	v_mfma_f32_16x16x32_bf16 v[96:99], v[174:177], v[192:195], v[96:99]
	v_mfma_f32_16x16x32_bf16 v[84:87], v[166:169], v[200:203], v[84:87]
	v_mfma_f32_16x16x32_bf16 v[80:83], v[174:177], v[200:203], v[80:83]
	v_mfma_f32_16x16x32_bf16 v[68:71], v[166:169], v[208:211], v[68:71]
	v_mfma_f32_16x16x32_bf16 v[64:67], v[174:177], v[208:211], v[64:67]
	v_mfma_f32_16x16x32_bf16 v[116:119], v[170:173], v[188:191], v[116:119]
	v_mfma_f32_16x16x32_bf16 v[112:115], v[178:181], v[188:191], v[112:115]
	v_mfma_f32_16x16x32_bf16 v[100:103], v[170:173], v[196:199], v[100:103]
	v_mfma_f32_16x16x32_bf16 v[96:99], v[178:181], v[196:199], v[96:99]
	v_mfma_f32_16x16x32_bf16 v[84:87], v[170:173], v[204:207], v[84:87]
	v_mfma_f32_16x16x32_bf16 v[80:83], v[178:181], v[204:207], v[80:83]
	v_mfma_f32_16x16x32_bf16 v[68:71], v[170:173], v[212:215], v[68:71]
	v_mfma_f32_16x16x32_bf16 v[64:67], v[178:181], v[212:215], v[64:67]
	s_setprio 0
	s_barrier
	s_mov_b32 m0, s27
	s_nop 0
	ds_read_b128 v[182:185], v157 offset:49152
	ds_read_b128 v[188:191], v157 offset:50176
	ds_read_b128 v[192:195], v157 offset:51200
	ds_read_b128 v[196:199], v157 offset:52224
	ds_read_b128 v[200:203], v157 offset:53248
	ds_read_b128 v[204:207], v157 offset:54272
	ds_read_b128 v[208:211], v157 offset:55296
	ds_read_b128 v[212:215], v157 offset:56320
	global_load_lds_dwordx4 v130, s[100:101]
	s_mov_b32 m0, s34
	s_nop 0
	global_load_lds_dwordx4 v134, s[100:101]
	s_mov_b32 m0, s35
	s_nop 0
	global_load_lds_dwordx4 v130, s[58:59]
	s_mov_b32 m0, s28
	s_nop 0
	global_load_lds_dwordx4 v134, s[58:59]
	s_mov_b32 m0, s92
	s_nop 0
	global_load_lds_dwordx4 v128, s[98:99]
	s_mov_b32 m0, s93
	s_nop 0
	global_load_lds_dwordx4 v132, s[98:99]
	s_waitcnt vmcnt(8)
	s_waitcnt lgkmcnt(0)
	s_barrier
	s_setprio 1
	s_waitcnt lgkmcnt(0)
	v_mfma_f32_16x16x32_bf16 v[60:63], v[144:147], v[182:185], v[60:63]
	v_mfma_f32_16x16x32_bf16 v[56:59], v[158:161], v[182:185], v[56:59]
	v_mfma_f32_16x16x32_bf16 v[44:47], v[144:147], v[192:195], v[44:47]
	v_mfma_f32_16x16x32_bf16 v[40:43], v[158:161], v[192:195], v[40:43]
	v_mfma_f32_16x16x32_bf16 v[28:31], v[144:147], v[200:203], v[28:31]
	v_mfma_f32_16x16x32_bf16 v[24:27], v[158:161], v[200:203], v[24:27]
	v_mfma_f32_16x16x32_bf16 v[12:15], v[144:147], v[208:211], v[12:15]
	v_mfma_f32_16x16x32_bf16 v[8:11], v[158:161], v[208:211], v[8:11]
	v_mfma_f32_16x16x32_bf16 v[60:63], v[148:151], v[188:191], v[60:63]
	v_mfma_f32_16x16x32_bf16 v[56:59], v[162:165], v[188:191], v[56:59]
	v_mfma_f32_16x16x32_bf16 v[44:47], v[148:151], v[196:199], v[44:47]
	v_mfma_f32_16x16x32_bf16 v[40:43], v[162:165], v[196:199], v[40:43]
	v_mfma_f32_16x16x32_bf16 v[28:31], v[148:151], v[204:207], v[28:31]
	v_mfma_f32_16x16x32_bf16 v[24:27], v[162:165], v[204:207], v[24:27]
	v_mfma_f32_16x16x32_bf16 v[12:15], v[148:151], v[212:215], v[12:15]
	v_mfma_f32_16x16x32_bf16 v[8:11], v[162:165], v[212:215], v[8:11]
	v_mfma_f32_16x16x32_bf16 v[52:55], v[166:169], v[182:185], v[52:55]
	v_mfma_f32_16x16x32_bf16 v[48:51], v[174:177], v[182:185], v[48:51]
	v_mfma_f32_16x16x32_bf16 v[36:39], v[166:169], v[192:195], v[36:39]
	v_mfma_f32_16x16x32_bf16 v[32:35], v[174:177], v[192:195], v[32:35]
	v_mfma_f32_16x16x32_bf16 v[20:23], v[166:169], v[200:203], v[20:23]
	v_mfma_f32_16x16x32_bf16 v[16:19], v[174:177], v[200:203], v[16:19]
	v_mfma_f32_16x16x32_bf16 v[4:7], v[166:169], v[208:211], v[4:7]
	v_mfma_f32_16x16x32_bf16 v[0:3], v[174:177], v[208:211], v[0:3]
	v_mfma_f32_16x16x32_bf16 v[52:55], v[170:173], v[188:191], v[52:55]
	v_mfma_f32_16x16x32_bf16 v[48:51], v[178:181], v[188:191], v[48:51]
	v_mfma_f32_16x16x32_bf16 v[36:39], v[170:173], v[196:199], v[36:39]
	v_mfma_f32_16x16x32_bf16 v[32:35], v[178:181], v[196:199], v[32:35]
	v_mfma_f32_16x16x32_bf16 v[20:23], v[170:173], v[204:207], v[20:23]
	v_mfma_f32_16x16x32_bf16 v[16:19], v[178:181], v[204:207], v[16:19]
	v_mfma_f32_16x16x32_bf16 v[4:7], v[170:173], v[212:215], v[4:7]
	v_mfma_f32_16x16x32_bf16 v[0:3], v[178:181], v[212:215], v[0:3]
	s_setprio 0
	s_barrier
	s_add_i32 s45, s45, 2
	s_add_u32 s50, s50, 0x100
	s_addc_u32 s51, s51, 0
	s_add_u32 s23, s23, 0x100
	s_addc_u32 s25, s25, 0
	s_cmp_gt_u32 s45, 29
	s_cbranch_scc0 .LBB0_413
	s_and_b64 vcc, exec, s[78:79]
	s_cbranch_vccz .LBB0_416
	s_barrier

.LBB0_674:
	ds_read_b128 v[128:131], v174
	ds_read_b128 v[132:135], v174 offset:1024
	ds_read_b128 v[148:151], v174 offset:2048
	ds_read_b128 v[152:155], v174 offset:3072
	ds_read_b128 v[156:159], v175
	ds_read_b128 v[160:163], v175 offset:1024
	ds_read_b128 v[164:167], v175 offset:2048
	ds_read_b128 v[168:171], v175 offset:3072
	s_add_u32 s36, s24, 0x4000
	s_addc_u32 s37, s25, 0
	s_cmpk_eq_i32 s45, 0x7c
	s_cselect_b32 s40, s29, s36
	s_cselect_b32 s41, s3, s37
	s_cselect_b32 s38, s4, s30
	s_cselect_b32 s39, s5, s31
	s_add_u32 s36, s40, 0x8000
	s_addc_u32 s37, s41, 0
	s_add_u32 s46, s38, 0x200000
	s_addc_u32 s47, s39, 0
	s_mov_b32 m0, s94
	ds_read_b128 v[182:185], v176
	ds_read_b128 v[188:191], v176 offset:1024
	ds_read_b128 v[192:195], v176 offset:2048
	ds_read_b128 v[196:199], v176 offset:3072
	ds_read_b128 v[200:203], v176 offset:4096
	ds_read_b128 v[204:207], v176 offset:5120
	ds_read_b128 v[208:211], v176 offset:6144
	ds_read_b128 v[212:215], v176 offset:7168
	global_load_lds_dwordx4 v144, s[24:25]
	s_mov_b32 m0, s95
	s_nop 0
	global_load_lds_dwordx4 v146, s[24:25]
	s_waitcnt vmcnt(8)
	s_waitcnt lgkmcnt(0)
	s_barrier
	s_setprio 1
	s_waitcnt lgkmcnt(0)
	v_mfma_f32_16x16x32_bf16 v[124:127], v[128:131], v[182:185], v[124:127]
	v_mfma_f32_16x16x32_bf16 v[120:123], v[148:151], v[182:185], v[120:123]
	v_mfma_f32_16x16x32_bf16 v[108:111], v[128:131], v[192:195], v[108:111]
	v_mfma_f32_16x16x32_bf16 v[104:107], v[148:151], v[192:195], v[104:107]
	v_mfma_f32_16x16x32_bf16 v[92:95], v[128:131], v[200:203], v[92:95]
	v_mfma_f32_16x16x32_bf16 v[88:91], v[148:151], v[200:203], v[88:91]
	v_mfma_f32_16x16x32_bf16 v[76:79], v[128:131], v[208:211], v[76:79]
	v_mfma_f32_16x16x32_bf16 v[72:75], v[148:151], v[208:211], v[72:75]
	v_mfma_f32_16x16x32_bf16 v[124:127], v[132:135], v[188:191], v[124:127]
	v_mfma_f32_16x16x32_bf16 v[120:123], v[152:155], v[188:191], v[120:123]
	v_mfma_f32_16x16x32_bf16 v[108:111], v[132:135], v[196:199], v[108:111]
	v_mfma_f32_16x16x32_bf16 v[104:107], v[152:155], v[196:199], v[104:107]
	v_mfma_f32_16x16x32_bf16 v[92:95], v[132:135], v[204:207], v[92:95]
	v_mfma_f32_16x16x32_bf16 v[88:91], v[152:155], v[204:207], v[88:91]
	v_mfma_f32_16x16x32_bf16 v[76:79], v[132:135], v[212:215], v[76:79]
	v_mfma_f32_16x16x32_bf16 v[72:75], v[152:155], v[212:215], v[72:75]
	v_mfma_f32_16x16x32_bf16 v[116:119], v[156:159], v[182:185], v[116:119]
	v_mfma_f32_16x16x32_bf16 v[112:115], v[164:167], v[182:185], v[112:115]
	v_mfma_f32_16x16x32_bf16 v[100:103], v[156:159], v[192:195], v[100:103]
	v_mfma_f32_16x16x32_bf16 v[96:99], v[164:167], v[192:195], v[96:99]
	v_mfma_f32_16x16x32_bf16 v[84:87], v[156:159], v[200:203], v[84:87]
	v_mfma_f32_16x16x32_bf16 v[80:83], v[164:167], v[200:203], v[80:83]
	v_mfma_f32_16x16x32_bf16 v[68:71], v[156:159], v[208:211], v[68:71]
	v_mfma_f32_16x16x32_bf16 v[64:67], v[164:167], v[208:211], v[64:67]
	v_mfma_f32_16x16x32_bf16 v[116:119], v[160:163], v[188:191], v[116:119]
	v_mfma_f32_16x16x32_bf16 v[112:115], v[168:171], v[188:191], v[112:115]
	v_mfma_f32_16x16x32_bf16 v[100:103], v[160:163], v[196:199], v[100:103]
	v_mfma_f32_16x16x32_bf16 v[96:99], v[168:171], v[196:199], v[96:99]
	v_mfma_f32_16x16x32_bf16 v[84:87], v[160:163], v[204:207], v[84:87]
	v_mfma_f32_16x16x32_bf16 v[80:83], v[168:171], v[204:207], v[80:83]
	v_mfma_f32_16x16x32_bf16 v[68:71], v[160:163], v[212:215], v[68:71]
	v_mfma_f32_16x16x32_bf16 v[64:67], v[168:171], v[212:215], v[64:67]
	s_setprio 0
	s_barrier
	s_mov_b32 m0, s96
	s_add_u32 s98, s40, 0x4000
	s_addc_u32 s99, s41, 0
	ds_read_b128 v[182:185], v176 offset:16384
	ds_read_b128 v[188:191], v176 offset:17408
	ds_read_b128 v[192:195], v176 offset:18432
	ds_read_b128 v[196:199], v176 offset:19456
	ds_read_b128 v[200:203], v176 offset:20480
	ds_read_b128 v[204:207], v176 offset:21504
	ds_read_b128 v[208:211], v176 offset:22528
	ds_read_b128 v[212:215], v176 offset:23552
	global_load_lds_dwordx4 v138, s[38:39]
	s_mov_b32 m0, s97
	s_nop 0
	global_load_lds_dwordx4 v142, s[38:39]
	s_mov_b32 m0, s91
	s_nop 0
	global_load_lds_dwordx4 v138, s[46:47]
	s_mov_b32 m0, s26
	s_nop 0
	global_load_lds_dwordx4 v142, s[46:47]
	s_mov_b32 m0, s33
	s_nop 0
	global_load_lds_dwordx4 v136, s[40:41]
	s_mov_b32 m0, s88
	s_nop 0
	global_load_lds_dwordx4 v140, s[40:41]
	s_waitcnt vmcnt(8)
	s_waitcnt lgkmcnt(0)
	s_barrier
	s_setprio 1
	s_waitcnt lgkmcnt(0)
	v_mfma_f32_16x16x32_bf16 v[60:63], v[128:131], v[182:185], v[60:63]
	v_mfma_f32_16x16x32_bf16 v[56:59], v[148:151], v[182:185], v[56:59]
	v_mfma_f32_16x16x32_bf16 v[44:47], v[128:131], v[192:195], v[44:47]
	v_mfma_f32_16x16x32_bf16 v[40:43], v[148:151], v[192:195], v[40:43]
	v_mfma_f32_16x16x32_bf16 v[28:31], v[128:131], v[200:203], v[28:31]
	v_mfma_f32_16x16x32_bf16 v[24:27], v[148:151], v[200:203], v[24:27]
	v_mfma_f32_16x16x32_bf16 v[12:15], v[128:131], v[208:211], v[12:15]
	v_mfma_f32_16x16x32_bf16 v[8:11], v[148:151], v[208:211], v[8:11]
	v_mfma_f32_16x16x32_bf16 v[60:63], v[132:135], v[188:191], v[60:63]
	v_mfma_f32_16x16x32_bf16 v[56:59], v[152:155], v[188:191], v[56:59]
	v_mfma_f32_16x16x32_bf16 v[44:47], v[132:135], v[196:199], v[44:47]
	v_mfma_f32_16x16x32_bf16 v[40:43], v[152:155], v[196:199], v[40:43]
	v_mfma_f32_16x16x32_bf16 v[28:31], v[132:135], v[204:207], v[28:31]
	v_mfma_f32_16x16x32_bf16 v[24:27], v[152:155], v[204:207], v[24:27]
	v_mfma_f32_16x16x32_bf16 v[12:15], v[132:135], v[212:215], v[12:15]
	v_mfma_f32_16x16x32_bf16 v[8:11], v[152:155], v[212:215], v[8:11]
	v_mfma_f32_16x16x32_bf16 v[52:55], v[156:159], v[182:185], v[52:55]
	v_mfma_f32_16x16x32_bf16 v[48:51], v[164:167], v[182:185], v[48:51]
	v_mfma_f32_16x16x32_bf16 v[36:39], v[156:159], v[192:195], v[36:39]
	v_mfma_f32_16x16x32_bf16 v[32:35], v[164:167], v[192:195], v[32:35]
	v_mfma_f32_16x16x32_bf16 v[20:23], v[156:159], v[200:203], v[20:23]
	v_mfma_f32_16x16x32_bf16 v[16:19], v[164:167], v[200:203], v[16:19]
	v_mfma_f32_16x16x32_bf16 v[4:7], v[156:159], v[208:211], v[4:7]
	v_mfma_f32_16x16x32_bf16 v[0:3], v[164:167], v[208:211], v[0:3]
	v_mfma_f32_16x16x32_bf16 v[52:55], v[160:163], v[188:191], v[52:55]
	v_mfma_f32_16x16x32_bf16 v[48:51], v[168:171], v[188:191], v[48:51]
	v_mfma_f32_16x16x32_bf16 v[36:39], v[160:163], v[196:199], v[36:39]
	v_mfma_f32_16x16x32_bf16 v[32:35], v[168:171], v[196:199], v[32:35]
	v_mfma_f32_16x16x32_bf16 v[20:23], v[160:163], v[204:207], v[20:23]
	v_mfma_f32_16x16x32_bf16 v[16:19], v[168:171], v[204:207], v[16:19]
	v_mfma_f32_16x16x32_bf16 v[4:7], v[160:163], v[212:215], v[4:7]
	v_mfma_f32_16x16x32_bf16 v[0:3], v[168:171], v[212:215], v[0:3]
	s_setprio 0
	s_barrier
	ds_read_b128 v[128:131], v179
	ds_read_b128 v[132:135], v179 offset:1024
	ds_read_b128 v[148:151], v179 offset:2048
	ds_read_b128 v[152:155], v179 offset:3072
	ds_read_b128 v[156:159], v180
	ds_read_b128 v[160:163], v180 offset:1024
	ds_read_b128 v[164:167], v180 offset:2048
	ds_read_b128 v[168:171], v180 offset:3072
	s_mov_b32 m0, s89
	s_add_u32 s100, s38, 0x80
	s_addc_u32 s101, s39, 0
	ds_read_b128 v[182:185], v176 offset:32768
	ds_read_b128 v[188:191], v176 offset:33792
	ds_read_b128 v[192:195], v176 offset:34816
	ds_read_b128 v[196:199], v176 offset:35840
	ds_read_b128 v[200:203], v176 offset:36864
	ds_read_b128 v[204:207], v176 offset:37888
	ds_read_b128 v[208:211], v176 offset:38912
	ds_read_b128 v[212:215], v176 offset:39936
	global_load_lds_dwordx4 v136, s[98:99]
	s_mov_b32 m0, s90
	s_add_u32 s46, s38, 0x200080
	s_addc_u32 s47, s39, 0
	global_load_lds_dwordx4 v140, s[98:99]
	s_waitcnt vmcnt(8)
	s_waitcnt lgkmcnt(0)
	s_barrier
	s_setprio 1
	s_waitcnt lgkmcnt(0)
	v_mfma_f32_16x16x32_bf16 v[124:127], v[128:131], v[182:185], v[124:127]
	v_mfma_f32_16x16x32_bf16 v[120:123], v[148:151], v[182:185], v[120:123]
	v_mfma_f32_16x16x32_bf16 v[108:111], v[128:131], v[192:195], v[108:111]
	v_mfma_f32_16x16x32_bf16 v[104:107], v[148:151], v[192:195], v[104:107]
	v_mfma_f32_16x16x32_bf16 v[92:95], v[128:131], v[200:203], v[92:95]
	v_mfma_f32_16x16x32_bf16 v[88:91], v[148:151], v[200:203], v[88:91]
	v_mfma_f32_16x16x32_bf16 v[76:79], v[128:131], v[208:211], v[76:79]
	v_mfma_f32_16x16x32_bf16 v[72:75], v[148:151], v[208:211], v[72:75]
	v_mfma_f32_16x16x32_bf16 v[124:127], v[132:135], v[188:191], v[124:127]
	v_mfma_f32_16x16x32_bf16 v[120:123], v[152:155], v[188:191], v[120:123]
	v_mfma_f32_16x16x32_bf16 v[108:111], v[132:135], v[196:199], v[108:111]
	v_mfma_f32_16x16x32_bf16 v[104:107], v[152:155], v[196:199], v[104:107]
	v_mfma_f32_16x16x32_bf16 v[92:95], v[132:135], v[204:207], v[92:95]
	v_mfma_f32_16x16x32_bf16 v[88:91], v[152:155], v[204:207], v[88:91]
	v_mfma_f32_16x16x32_bf16 v[76:79], v[132:135], v[212:215], v[76:79]
	v_mfma_f32_16x16x32_bf16 v[72:75], v[152:155], v[212:215], v[72:75]
	v_mfma_f32_16x16x32_bf16 v[116:119], v[156:159], v[182:185], v[116:119]
	v_mfma_f32_16x16x32_bf16 v[112:115], v[164:167], v[182:185], v[112:115]
	v_mfma_f32_16x16x32_bf16 v[100:103], v[156:159], v[192:195], v[100:103]
	v_mfma_f32_16x16x32_bf16 v[96:99], v[164:167], v[192:195], v[96:99]
	v_mfma_f32_16x16x32_bf16 v[84:87], v[156:159], v[200:203], v[84:87]
	v_mfma_f32_16x16x32_bf16 v[80:83], v[164:167], v[200:203], v[80:83]
	v_mfma_f32_16x16x32_bf16 v[68:71], v[156:159], v[208:211], v[68:71]
	v_mfma_f32_16x16x32_bf16 v[64:67], v[164:167], v[208:211], v[64:67]
	v_mfma_f32_16x16x32_bf16 v[116:119], v[160:163], v[188:191], v[116:119]
	v_mfma_f32_16x16x32_bf16 v[112:115], v[168:171], v[188:191], v[112:115]
	v_mfma_f32_16x16x32_bf16 v[100:103], v[160:163], v[196:199], v[100:103]
	v_mfma_f32_16x16x32_bf16 v[96:99], v[168:171], v[196:199], v[96:99]
	v_mfma_f32_16x16x32_bf16 v[84:87], v[160:163], v[204:207], v[84:87]
	v_mfma_f32_16x16x32_bf16 v[80:83], v[168:171], v[204:207], v[80:83]
	v_mfma_f32_16x16x32_bf16 v[68:71], v[160:163], v[212:215], v[68:71]
	v_mfma_f32_16x16x32_bf16 v[64:67], v[168:171], v[212:215], v[64:67]
	s_setprio 0
	s_barrier
	s_mov_b32 m0, s27
	s_nop 0
	ds_read_b128 v[182:185], v176 offset:49152
	ds_read_b128 v[188:191], v176 offset:50176
	ds_read_b128 v[192:195], v176 offset:51200
	ds_read_b128 v[196:199], v176 offset:52224
	ds_read_b128 v[200:203], v176 offset:53248
	ds_read_b128 v[204:207], v176 offset:54272
	ds_read_b128 v[208:211], v176 offset:55296
	ds_read_b128 v[212:215], v176 offset:56320
	global_load_lds_dwordx4 v138, s[100:101]
	s_mov_b32 m0, s34
	s_nop 0
	global_load_lds_dwordx4 v142, s[100:101]
	s_mov_b32 m0, s35
	s_nop 0
	global_load_lds_dwordx4 v138, s[46:47]
	s_mov_b32 m0, s28
	s_nop 0
	global_load_lds_dwordx4 v142, s[46:47]
	s_mov_b32 m0, s92
	s_nop 0
	global_load_lds_dwordx4 v136, s[36:37]
	s_mov_b32 m0, s93
	s_nop 0
	global_load_lds_dwordx4 v140, s[36:37]
	s_waitcnt vmcnt(8)
	s_waitcnt lgkmcnt(0)
	s_barrier
	s_setprio 1
	s_waitcnt lgkmcnt(0)
	v_mfma_f32_16x16x32_bf16 v[60:63], v[128:131], v[182:185], v[60:63]
	v_mfma_f32_16x16x32_bf16 v[56:59], v[148:151], v[182:185], v[56:59]
	v_mfma_f32_16x16x32_bf16 v[44:47], v[128:131], v[192:195], v[44:47]
	v_mfma_f32_16x16x32_bf16 v[40:43], v[148:151], v[192:195], v[40:43]
	v_mfma_f32_16x16x32_bf16 v[28:31], v[128:131], v[200:203], v[28:31]
	v_mfma_f32_16x16x32_bf16 v[24:27], v[148:151], v[200:203], v[24:27]
	v_mfma_f32_16x16x32_bf16 v[12:15], v[128:131], v[208:211], v[12:15]
	v_mfma_f32_16x16x32_bf16 v[8:11], v[148:151], v[208:211], v[8:11]
	v_mfma_f32_16x16x32_bf16 v[60:63], v[132:135], v[188:191], v[60:63]
	v_mfma_f32_16x16x32_bf16 v[56:59], v[152:155], v[188:191], v[56:59]
	v_mfma_f32_16x16x32_bf16 v[44:47], v[132:135], v[196:199], v[44:47]
	v_mfma_f32_16x16x32_bf16 v[40:43], v[152:155], v[196:199], v[40:43]
	v_mfma_f32_16x16x32_bf16 v[28:31], v[132:135], v[204:207], v[28:31]
	v_mfma_f32_16x16x32_bf16 v[24:27], v[152:155], v[204:207], v[24:27]
	v_mfma_f32_16x16x32_bf16 v[12:15], v[132:135], v[212:215], v[12:15]
	v_mfma_f32_16x16x32_bf16 v[8:11], v[152:155], v[212:215], v[8:11]
	v_mfma_f32_16x16x32_bf16 v[52:55], v[156:159], v[182:185], v[52:55]
	v_mfma_f32_16x16x32_bf16 v[48:51], v[164:167], v[182:185], v[48:51]
	v_mfma_f32_16x16x32_bf16 v[36:39], v[156:159], v[192:195], v[36:39]
	v_mfma_f32_16x16x32_bf16 v[32:35], v[164:167], v[192:195], v[32:35]
	v_mfma_f32_16x16x32_bf16 v[20:23], v[156:159], v[200:203], v[20:23]
	v_mfma_f32_16x16x32_bf16 v[16:19], v[164:167], v[200:203], v[16:19]
	v_mfma_f32_16x16x32_bf16 v[4:7], v[156:159], v[208:211], v[4:7]
	v_mfma_f32_16x16x32_bf16 v[0:3], v[164:167], v[208:211], v[0:3]
	v_mfma_f32_16x16x32_bf16 v[52:55], v[160:163], v[188:191], v[52:55]
	v_mfma_f32_16x16x32_bf16 v[48:51], v[168:171], v[188:191], v[48:51]
	v_mfma_f32_16x16x32_bf16 v[36:39], v[160:163], v[196:199], v[36:39]
	v_mfma_f32_16x16x32_bf16 v[32:35], v[168:171], v[196:199], v[32:35]
	v_mfma_f32_16x16x32_bf16 v[20:23], v[160:163], v[204:207], v[20:23]
	v_mfma_f32_16x16x32_bf16 v[16:19], v[168:171], v[204:207], v[16:19]
	v_mfma_f32_16x16x32_bf16 v[4:7], v[160:163], v[212:215], v[4:7]
	v_mfma_f32_16x16x32_bf16 v[0:3], v[168:171], v[212:215], v[0:3]
	s_setprio 0
	s_barrier
	s_add_i32 s45, s45, 2
	s_add_u32 s30, s30, 0x100
	s_addc_u32 s31, s31, 0
	s_add_u32 s24, s24, 0x10000
	s_addc_u32 s25, s25, 0
	s_cmpk_gt_u32 s45, 0x7d
	s_cbranch_scc0 .LBB0_674
	s_and_b64 vcc, exec, s[78:79]
	s_cbranch_vccz .LBB0_677
	s_barrier
